# v13
# speedup vs baseline: 1.3150x; 1.0157x over previous
.LBB0_287:
	v_readlane_b32 s6, v227, 7
	v_mov_b32_e32 v0, v178
	v_readlane_b32 s7, v227, 8
	s_andn2_b64 vcc, exec, s[6:7]
	v_readfirstlane_b32 s2, v0
	s_cbranch_vccnz .LBB0_416
	v_readlane_b32 s8, v227, 55
	v_readlane_b32 s11, v227, 58
	v_readlane_b32 s10, v227, 57
	s_ashr_i32 s7, s11, 31
	s_mov_b32 s6, s11
	s_lshl_b64 s[6:7], s[6:7], 20
	s_ashr_i32 s8, s2, 6
	s_lshr_b32 s24, s22, 6
	s_and_b32 s25, s2, 0xc0
	v_readlane_b32 s10, v227, 49
	v_readlane_b32 s11, v227, 50
	s_cmp_lg_u32 s10, 16
	v_readlane_b32 s12, v227, 51
	s_cselect_b64 s[10:11], -1, 0
	v_readlane_b32 s13, v227, 52
	s_add_u32 s18, s12, s6
	v_readlane_b32 s6, v227, 38
	s_addc_u32 s19, s13, s7
	s_ashr_i32 s2, s2, 1
	s_mul_hi_i32 s7, s6, s22
	s_mul_i32 s6, s6, s22
	v_bfe_u32 v2, v0, 3, 3
	s_and_b32 s2, s2, 0xffffff80
	s_lshl_b64 s[6:7], s[6:7], 1
	v_readlane_b32 s9, v227, 56
	v_lshl_or_b32 v2, s8, 3, v2
	s_add_u32 s64, s60, s6
	v_readlane_b32 s6, v227, 39
	v_lshrrev_b32_e32 v3, 1, v2
	s_addc_u32 s9, s61, s7
	s_mul_hi_i32 s7, s6, s22
	s_mul_i32 s6, s6, s22
	v_xor_b32_e32 v3, v3, v0
	s_lshl_b64 s[6:7], s[6:7], 1
	v_lshlrev_b32_e32 v3, 3, v3
	v_mul_lo_u32 v2, v2, s22
	s_add_u32 s12, s96, s6
	v_and_or_b32 v2, v3, 56, v2
	s_addc_u32 s6, s97, s7
	s_lshl_b32 s26, s8, 10
	v_lshlrev_b32_e32 v131, 1, v2
	s_and_b32 s65, s9, 0xffff
	s_add_i32 s28, s26, 0x8000
	s_mov_b32 m0, s26
	s_and_b32 s13, s6, 0xffff
	s_mov_b32 s14, s66
	s_mov_b32 s15, s67
	v_bfe_u32 v248, v178, 3, 3
	s_and_b32 s6, s8, 1
	s_lshl_b32 s6, s6, 5
	s_lshr_b32 s7, s8, 1
	s_add_i32 s6, s6, s7
	v_lshl_add_u32 v248, v248, 2, s6
	v_mul_lo_u32 v248, v248, s22
	v_and_or_b32 v248, v3, 56, v248
	v_lshlrev_b32_e32 v248, 1, v248
	buffer_load_dwordx4 v131, s[64:67], 0 offen lds
	s_mov_b32 m0, s28
	s_add_i32 s29, s26, 0x2000
	s_lshl_b32 s27, s22, 7
	buffer_load_dwordx4 v248, s[12:15], 0 offen lds
	s_mov_b32 m0, s29
	s_add_i32 s30, s26, 0xa000
	buffer_load_dwordx4 v131, s[64:67], s27 offen lds
	s_mov_b32 m0, s30
	s_add_i32 s31, s26, 0x4000
	buffer_load_dwordx4 v248, s[12:15], s27 offen lds
	s_lshl_b32 s34, s22, 8
	s_mov_b32 m0, s31
	s_add_i32 s35, s26, 0xc000
	buffer_load_dwordx4 v131, s[64:67], s34 offen lds
	s_mov_b32 m0, s35
	s_add_i32 s36, s26, 0x6000
	buffer_load_dwordx4 v248, s[12:15], s34 offen lds
	s_mul_i32 s37, s22, 0x180
	s_mov_b32 m0, s36
	s_add_i32 s38, s26, 0xe000
	buffer_load_dwordx4 v131, s[64:67], s37 offen lds
	s_mov_b32 m0, s38
	v_and_b32_e32 v130, 15, v0
	buffer_load_dwordx4 v248, s[12:15], s37 offen lds
	v_or_b32_e32 v2, s25, v130
	v_bfe_u32 v3, v0, 4, 2
	v_lshrrev_b32_e32 v4, 1, v0
	v_lshlrev_b32_e32 v0, 7, v0
	v_lshlrev_b32_e32 v2, 7, v2
	v_bitop3_b32 v4, v3, v4, 7 bitop3:0x78
	v_and_b32_e32 v0, 0x380, v0
	v_or_b32_e32 v5, s2, v130
	v_and_b32_e32 v2, 0x6400, v2
	v_lshlrev_b32_e32 v5, 7, v5
	v_lshl_or_b32 v0, v4, 4, v0
	s_mov_b32 s6, 0x8000
	v_lshl_or_b32 v142, v3, 2, s2
	s_movk_i32 s2, 0xc400
	v_or3_b32 v133, v2, v0, s6
	v_cmp_eq_u32_e64 s[6:7], 2, v130
	v_cmp_gt_u32_e64 s[8:9], 4, v130
	v_lshlrev_b32_e32 v132, 4, v130
	v_and_or_b32 v143, v5, s2, v0
	s_lshl_b32 s39, s24, 16
	s_mov_b32 s40, s72
	s_branch .LBB0_290

.LBB0_296:
	s_and_b32 s2, s44, 0x10000
	s_cmp_ge_u32 s41, s24
	s_xor_b32 s14, s2, 0x10000
	s_add_i32 s46, s26, s14
	s_add_i32 s47, s46, 0x8000
	s_mov_b32 s14, s66
	s_mov_b32 s15, s67
	s_waitcnt lgkmcnt(0)
	v_add_u32_e32 v228, s2, v143
	v_add_u32_e32 v229, s2, v133
	ds_read_b128 v[134:137], v229 offset:0
	ds_read_b128 v[138:141], v229 offset:0x800
	ds_read_b128 v[144:147], v229 offset:0x1000
	ds_read_b128 v[148:151], v229 offset:0x1800
	ds_read_b128 v[152:155], v228 offset:0
	ds_read_b128 v[156:159], v228 offset:0x800
	s_setprio 1
	s_mov_b32 m0, s46
	s_nop 0
	buffer_load_dwordx4 v131, s[64:67], s45 offen lds
	s_mov_b32 m0, s47
	s_add_i32 s47, s27, s45
	buffer_load_dwordx4 v248, s[12:15], s45 offen lds
	s_add_i32 m0, s46, 0x2000
	s_nop 0
	buffer_load_dwordx4 v131, s[64:67], s47 offen lds
	s_add_i32 m0, s46, 0xa000
	s_nop 0
	buffer_load_dwordx4 v248, s[12:15], s47 offen lds
	ds_read_b128 v[160:163], v228 offset:0x1000
	v_xor_b32_e32 v176, 64, v228
	s_branch .Lrot1_mid_l
.Lrot1_top_l:
	s_xor_b32 s14, s2, 0x10000
	s_add_i32 s46, s26, s14
	s_add_i32 s47, s46, 0x8000
	s_mov_b32 s14, s66
	s_mov_b32 s15, s67
	v_add_u32_e32 v228, s2, v143
	v_add_u32_e32 v229, s2, v133
	ds_read_b128 v[134:137], v229 offset:0
	ds_read_b128 v[138:141], v229 offset:0x800
	ds_read_b128 v[144:147], v229 offset:0x1000
	ds_read_b128 v[148:151], v229 offset:0x1800
	ds_read_b128 v[152:155], v228 offset:0
	ds_read_b128 v[156:159], v228 offset:0x800
	s_setprio 1
	s_mov_b32 m0, s46
	s_nop 0
	buffer_load_dwordx4 v131, s[64:67], s45 offen lds
	s_mov_b32 m0, s47
	s_add_i32 s47, s27, s45
	buffer_load_dwordx4 v248, s[12:15], s45 offen lds
	v_mfma_f32_16x16x32_bf16 v[46:49], v[236:239], v[160:163], v[46:49]
	v_mfma_f32_16x16x32_bf16 v[42:45], v[236:239], v[164:167], v[42:45]
	v_mfma_f32_16x16x32_bf16 v[38:41], v[236:239], v[168:171], v[38:41]
	v_mfma_f32_16x16x32_bf16 v[34:37], v[236:239], v[232:235], v[34:37]
	s_add_i32 m0, s46, 0x2000
	s_nop 0
	buffer_load_dwordx4 v131, s[64:67], s47 offen lds
	v_mfma_f32_16x16x32_bf16 v[30:33], v[240:243], v[160:163], v[30:33]
	v_mfma_f32_16x16x32_bf16 v[26:29], v[240:243], v[164:167], v[26:29]
	v_mfma_f32_16x16x32_bf16 v[22:25], v[240:243], v[168:171], v[22:25]
	v_mfma_f32_16x16x32_bf16 v[18:21], v[240:243], v[232:235], v[18:21]
	s_add_i32 m0, s46, 0xa000
	s_nop 0
	buffer_load_dwordx4 v248, s[12:15], s47 offen lds
	v_mfma_f32_16x16x32_bf16 v[14:17], v[244:247], v[160:163], v[14:17]
	v_mfma_f32_16x16x32_bf16 v[10:13], v[244:247], v[164:167], v[10:13]
	v_mfma_f32_16x16x32_bf16 v[6:9], v[244:247], v[168:171], v[6:9]
	v_mfma_f32_16x16x32_bf16 v[2:5], v[244:247], v[232:235], v[2:5]
	ds_read_b128 v[160:163], v228 offset:0x1000
	v_xor_b32_e32 v176, 64, v228
.Lrot1_mid_l:
	s_waitcnt lgkmcnt(2)
	s_nop 0
	v_mfma_f32_16x16x32_bf16 v[126:129], v[152:155], v[134:137], v[126:129]
	v_mfma_f32_16x16x32_bf16 v[122:125], v[152:155], v[138:141], v[122:125]
	v_mfma_f32_16x16x32_bf16 v[118:121], v[152:155], v[144:147], v[118:121]
	v_mfma_f32_16x16x32_bf16 v[114:117], v[152:155], v[148:151], v[114:117]
	s_add_i32 m0, s46, 0x4000
	s_add_i32 s47, s34, s45
	buffer_load_dwordx4 v131, s[64:67], s47 offen lds
	ds_read_b128 v[152:155], v228 offset:0x1800
	s_waitcnt lgkmcnt(2)
	s_nop 0
	v_mfma_f32_16x16x32_bf16 v[110:113], v[156:159], v[134:137], v[110:113]
	v_mfma_f32_16x16x32_bf16 v[106:109], v[156:159], v[138:141], v[106:109]
	v_mfma_f32_16x16x32_bf16 v[102:105], v[156:159], v[144:147], v[102:105]
	v_mfma_f32_16x16x32_bf16 v[98:101], v[156:159], v[148:151], v[98:101]
	s_add_i32 m0, s46, 0xc000
	s_nop 0
	buffer_load_dwordx4 v248, s[12:15], s47 offen lds
	ds_read_b128 v[156:159], v228 offset:0x2000
	s_waitcnt lgkmcnt(2)
	s_nop 0
	v_mfma_f32_16x16x32_bf16 v[94:97], v[160:163], v[134:137], v[94:97]
	v_mfma_f32_16x16x32_bf16 v[90:93], v[160:163], v[138:141], v[90:93]
	v_mfma_f32_16x16x32_bf16 v[86:89], v[160:163], v[144:147], v[86:89]
	v_mfma_f32_16x16x32_bf16 v[82:85], v[160:163], v[148:151], v[82:85]
	s_add_i32 m0, s46, 0x6000
	s_add_i32 s47, s37, s45
	buffer_load_dwordx4 v131, s[64:67], s47 offen lds
	ds_read_b128 v[160:163], v228 offset:0x2800
	s_waitcnt lgkmcnt(2)
	s_nop 0
	v_mfma_f32_16x16x32_bf16 v[78:81], v[152:155], v[134:137], v[78:81]
	v_mfma_f32_16x16x32_bf16 v[74:77], v[152:155], v[138:141], v[74:77]
	v_mfma_f32_16x16x32_bf16 v[70:73], v[152:155], v[144:147], v[70:73]
	v_mfma_f32_16x16x32_bf16 v[66:69], v[152:155], v[148:151], v[66:69]
	s_add_i32 m0, s46, 0xe000
	s_nop 0
	buffer_load_dwordx4 v248, s[12:15], s47 offen lds
	ds_read_b128 v[152:155], v228 offset:0x3000
	s_waitcnt lgkmcnt(2)
	s_nop 0
	v_mfma_f32_16x16x32_bf16 v[62:65], v[156:159], v[134:137], v[62:65]
	v_mfma_f32_16x16x32_bf16 v[58:61], v[156:159], v[138:141], v[58:61]
	v_mfma_f32_16x16x32_bf16 v[54:57], v[156:159], v[144:147], v[54:57]
	v_mfma_f32_16x16x32_bf16 v[50:53], v[156:159], v[148:151], v[50:53]
	ds_read_b128 v[156:159], v228 offset:0x3800
	s_waitcnt lgkmcnt(2)
	v_xor_b32_e32 v0, 64, v229
	v_mfma_f32_16x16x32_bf16 v[46:49], v[160:163], v[134:137], v[46:49]
	v_mfma_f32_16x16x32_bf16 v[42:45], v[160:163], v[138:141], v[42:45]
	v_mfma_f32_16x16x32_bf16 v[38:41], v[160:163], v[144:147], v[38:41]
	v_mfma_f32_16x16x32_bf16 v[34:37], v[160:163], v[148:151], v[34:37]
	ds_read_b128 v[160:163], v0 offset:0
	ds_read_b128 v[164:167], v0 offset:0x800
	ds_read_b128 v[168:171], v0 offset:0x1000
	s_waitcnt lgkmcnt(4)
	s_nop 0
	v_mfma_f32_16x16x32_bf16 v[30:33], v[152:155], v[134:137], v[30:33]
	v_mfma_f32_16x16x32_bf16 v[26:29], v[152:155], v[138:141], v[26:29]
	v_mfma_f32_16x16x32_bf16 v[22:25], v[152:155], v[144:147], v[22:25]
	v_mfma_f32_16x16x32_bf16 v[18:21], v[152:155], v[148:151], v[18:21]
	ds_read_b128 v[232:235], v0 offset:0x1800
	ds_read_b128 v[172:175], v176 offset:0
	ds_read_b128 v[202:205], v176 offset:0x800
	s_waitcnt lgkmcnt(6)
	s_nop 0
	v_mfma_f32_16x16x32_bf16 v[14:17], v[156:159], v[134:137], v[14:17]
	v_mfma_f32_16x16x32_bf16 v[10:13], v[156:159], v[138:141], v[10:13]
	v_mfma_f32_16x16x32_bf16 v[6:9], v[156:159], v[144:147], v[6:9]
	v_mfma_f32_16x16x32_bf16 v[2:5], v[156:159], v[148:151], v[2:5]
	ds_read_b128 v[134:137], v176 offset:0x1000
	s_waitcnt lgkmcnt(2)
	s_nop 0
	v_mfma_f32_16x16x32_bf16 v[126:129], v[172:175], v[160:163], v[126:129]
	v_mfma_f32_16x16x32_bf16 v[122:125], v[172:175], v[164:167], v[122:125]
	v_mfma_f32_16x16x32_bf16 v[118:121], v[172:175], v[168:171], v[118:121]
	v_mfma_f32_16x16x32_bf16 v[114:117], v[172:175], v[232:235], v[114:117]
	ds_read_b128 v[138:141], v176 offset:0x1800
	s_waitcnt lgkmcnt(2)
	s_nop 0
	v_mfma_f32_16x16x32_bf16 v[110:113], v[202:205], v[160:163], v[110:113]
	v_mfma_f32_16x16x32_bf16 v[106:109], v[202:205], v[164:167], v[106:109]
	v_mfma_f32_16x16x32_bf16 v[102:105], v[202:205], v[168:171], v[102:105]
	v_mfma_f32_16x16x32_bf16 v[98:101], v[202:205], v[232:235], v[98:101]
	ds_read_b128 v[144:147], v176 offset:0x2000
	ds_read_b128 v[236:239], v176 offset:0x2800
	s_waitcnt lgkmcnt(3)
	s_nop 0
	v_mfma_f32_16x16x32_bf16 v[94:97], v[134:137], v[160:163], v[94:97]
	v_mfma_f32_16x16x32_bf16 v[90:93], v[134:137], v[164:167], v[90:93]
	v_mfma_f32_16x16x32_bf16 v[86:89], v[134:137], v[168:171], v[86:89]
	v_mfma_f32_16x16x32_bf16 v[82:85], v[134:137], v[232:235], v[82:85]
	ds_read_b128 v[240:243], v176 offset:0x3000
	s_waitcnt lgkmcnt(3)
	s_nop 0
	v_mfma_f32_16x16x32_bf16 v[78:81], v[138:141], v[160:163], v[78:81]
	v_mfma_f32_16x16x32_bf16 v[74:77], v[138:141], v[164:167], v[74:77]
	v_mfma_f32_16x16x32_bf16 v[70:73], v[138:141], v[168:171], v[70:73]
	v_mfma_f32_16x16x32_bf16 v[66:69], v[138:141], v[232:235], v[66:69]
	ds_read_b128 v[244:247], v176 offset:0x3800
	s_waitcnt lgkmcnt(3)
	s_nop 0
	v_mfma_f32_16x16x32_bf16 v[62:65], v[144:147], v[160:163], v[62:65]
	v_mfma_f32_16x16x32_bf16 v[58:61], v[144:147], v[164:167], v[58:61]
	v_mfma_f32_16x16x32_bf16 v[54:57], v[144:147], v[168:171], v[54:57]
	v_mfma_f32_16x16x32_bf16 v[50:53], v[144:147], v[232:235], v[50:53]
	s_setprio 0
	s_waitcnt lgkmcnt(0)
	s_waitcnt vmcnt(0)
	s_add_i32 s44, s44, 0x10000
	s_addk_i32 s45, 0x80
	s_add_i32 s41, s41, 1
	s_and_b32 s2, s44, 0x10000
	s_cmp_ge_u32 s41, s24
	s_barrier
	s_cbranch_scc0 .Lrot1_top_l

.LBB0_298:
	v_add_u32_e32 v136, s20, v142
	s_or_b32 s12, s21, s25
	v_ashrrev_i32_e32 v137, 31, v136
	v_lshlrev_b64 v[134:135], 10, v[136:137]
	s_ashr_i32 s13, s12, 31
	v_lshl_add_u64 v[138:139], v[134:135], 0, s[12:13]
	v_or_b32_e32 v138, v138, v130
	v_lshl_add_u64 v[140:141], v[138:139], 1, s[94:95]
	v_lshlrev_b64 v[136:137], 6, v[136:137]
	s_ashr_i32 s12, s12, 6
	v_lshl_add_u64 v[134:135], v[138:139], 2, s[68:69]
	v_lshl_add_u64 v[136:137], s[18:19], 0, v[136:137]
	s_ashr_i32 s13, s12, 31
	v_mov_b64_e32 v[138:139], v[140:141]
	s_waitcnt vmcnt(0)
	v_lshl_add_u64 v[136:137], s[12:13], 2, v[136:137]
	s_waitcnt vmcnt(0)
	s_nop 1
	s_nop 0
	s_nop 1
	s_load_dword s2, s[78:79], 0x0
	s_waitcnt lgkmcnt(0)
	s_add_i32 s40, s2, s40
	s_cmpk_gt_i32 s40, 0xff
	s_cselect_b64 s[12:13], -1, 0
	s_cmpk_lt_i32 s40, 0x100
	s_cbranch_scc0 .LBB0_304
	s_ashr_i32 s2, s40, 31
	s_lshr_b32 s2, s2, 29
	s_add_i32 s2, s40, s2
	s_and_b32 s14, s2, -8
	s_sub_i32 s21, s40, s14
	s_cmp_gt_i32 s21, -1
	s_mov_b64 s[14:15], -1
	s_cbranch_scc0 .LBB0_301
	s_lshl_b32 s20, s21, 5
	s_mov_b64 s[14:15], 0

.LBB0_303:
	s_ashr_i32 s2, s2, 3
	s_add_i32 s2, s20, s2
	s_ashr_i32 s14, s2, 31
	s_lshr_b32 s14, s14, 28
	s_add_i32 s14, s2, s14
	s_and_b32 s15, s14, 0xfff0
	s_sub_i32 s2, s2, s15
	s_bfe_i32 s15, s2, 0x80000
	s_bfe_u32 s15, s15, 0x2000d
	s_add_i32 s15, s2, s15
	s_bfe_i32 s20, s15, 0x80000
	s_and_b32 s15, s15, 0xfc
	s_sub_i32 s2, s2, s15
	s_sext_i32_i8 s2, s2
	s_lshl_b32 s14, s14, 6
	s_sext_i32_i16 s20, s20
	s_and_b32 s14, s14, 0xfffffc00
	s_lshl_b32 s2, s2, 8
	s_add_i32 s2, s2, s14
	s_lshl_b32 s14, s20, 6
	s_and_b32 s20, s14, 0xffffff00
	s_mul_hi_i32 s15, s2, s22
	s_mul_i32 s14, s2, s22
	s_lshl_b64 s[14:15], s[14:15], 1
	s_add_u32 s64, s60, s14
	s_addc_u32 s2, s61, s15
	s_mul_hi_i32 s15, s20, s22
	s_mul_i32 s14, s20, s22
	s_lshl_b64 s[14:15], s[14:15], 1
	s_add_u32 s44, s96, s14
	s_mov_b32 m0, s26
	s_addc_u32 s14, s97, s15
	s_and_b32 s65, s2, 0xffff
	s_and_b32 s45, s14, 0xffff
	s_mov_b32 s46, s66
	s_mov_b32 s47, s67
	buffer_load_dwordx4 v131, s[64:67], 0 offen lds
	s_mov_b32 m0, s28
	s_nop 0
	buffer_load_dwordx4 v248, s[44:47], 0 offen lds
	s_mov_b32 m0, s29
	s_nop 0
	buffer_load_dwordx4 v131, s[64:67], s27 offen lds
	s_mov_b32 m0, s30
	s_nop 0
	buffer_load_dwordx4 v248, s[44:47], s27 offen lds
	s_mov_b32 m0, s31
	s_nop 0
	buffer_load_dwordx4 v131, s[64:67], s34 offen lds
	s_mov_b32 m0, s35
	s_nop 0
	buffer_load_dwordx4 v248, s[44:47], s34 offen lds
	s_mov_b32 m0, s36
	s_nop 0
	buffer_load_dwordx4 v131, s[64:67], s37 offen lds
	s_mov_b32 m0, s38
	s_nop 0
	buffer_load_dwordx4 v248, s[44:47], s37 offen lds
.LBB0_304:
	v_mul_u32_u24_e32 v254, 6, v130
	v_add_u32_e32 v254, 0x1000, v254
	v_mov_b32_e32 v255, 0
	v_lshl_add_u64 v[246:247], v[140:141], 0, v[254:255]
	v_mov_b64_e32 v[252:253], v[246:247]
	s_and_b64 vcc, exec, s[10:11]
	s_cbranch_vccz .Lresid_f32
	v_and_b32_e32 v254, 3, v130
	v_cmp_eq_u32_e64 vcc, 1, v254
	v_cmp_eq_u32_e64 s[14:15], 2, v254
	v_cmp_eq_u32_e64 s[20:21], 3, v254
	v_lshlrev_b32_e32 v254, 6, v254
	v_mov_b32_e32 v255, 0
	v_lshl_add_u64 v[250:251], v[136:137], 0, v[254:255]
	global_load_dwordx2 v[144:145], v[252:253], off offset:-4096
	global_load_dwordx2 v[146:147], v[252:253], off offset:-2048
	global_load_dwordx2 v[148:149], v[252:253], off offset:0
	global_load_dwordx2 v[150:151], v[252:253], off offset:2048
	v_lshl_add_u64 v[252:253], v[252:253], 0, s[92:93]
	global_load_dwordx2 v[152:153], v[252:253], off offset:-4096
	global_load_dwordx2 v[154:155], v[252:253], off offset:-2048
	global_load_dwordx2 v[156:157], v[252:253], off offset:0
	global_load_dwordx2 v[158:159], v[252:253], off offset:2048
	v_lshl_add_u64 v[252:253], v[252:253], 0, s[92:93]
	global_load_dwordx2 v[160:161], v[252:253], off offset:-4096
	global_load_dwordx2 v[162:163], v[252:253], off offset:-2048
	global_load_dwordx2 v[164:165], v[252:253], off offset:0
	global_load_dwordx2 v[166:167], v[252:253], off offset:2048
	v_lshl_add_u64 v[252:253], v[252:253], 0, s[92:93]
	global_load_dwordx2 v[168:169], v[252:253], off offset:-4096
	global_load_dwordx2 v[170:171], v[252:253], off offset:-2048
	global_load_dwordx2 v[172:173], v[252:253], off offset:0
	global_load_dwordx2 v[174:175], v[252:253], off offset:2048
	v_lshl_add_u64 v[252:253], v[252:253], 0, s[92:93]
	s_waitcnt vmcnt(12)
	v_lshlrev_b32_e32 v228, 16, v144
	v_and_b32_e32 v229, 0xffff0000, v144
	v_lshlrev_b32_e32 v230, 16, v145
	v_and_b32_e32 v231, 0xffff0000, v145
	v_fmac_f32_e32 v228, s23, v126
	v_fmac_f32_e32 v229, s23, v122
	v_fmac_f32_e32 v230, s23, v118
	v_fmac_f32_e32 v231, s23, v114
	v_cvt_pk_bf16_f32 v232, v228, v229
	v_cvt_pk_bf16_f32 v233, v230, v231
	global_store_dwordx2 v[246:247], v[232:233], off offset:-4096
	v_lshlrev_b32_e32 v228, 16, v232
	v_and_b32_e32 v229, 0xffff0000, v232
	v_lshlrev_b32_e32 v230, 16, v233
	v_and_b32_e32 v231, 0xffff0000, v233
	v_mul_f32_e32 v240, v228, v228
	v_fmac_f32_e32 v240, v229, v229
	v_fmac_f32_e32 v240, v230, v230
	v_fmac_f32_e32 v240, v231, v231
	v_lshlrev_b32_e32 v228, 16, v146
	v_and_b32_e32 v229, 0xffff0000, v146
	v_lshlrev_b32_e32 v230, 16, v147
	v_and_b32_e32 v231, 0xffff0000, v147
	v_fmac_f32_e32 v228, s23, v127
	v_fmac_f32_e32 v229, s23, v123
	v_fmac_f32_e32 v230, s23, v119
	v_fmac_f32_e32 v231, s23, v115
	v_cvt_pk_bf16_f32 v234, v228, v229
	v_cvt_pk_bf16_f32 v235, v230, v231
	global_store_dwordx2 v[246:247], v[234:235], off offset:-2048
	v_lshlrev_b32_e32 v228, 16, v234
	v_and_b32_e32 v229, 0xffff0000, v234
	v_lshlrev_b32_e32 v230, 16, v235
	v_and_b32_e32 v231, 0xffff0000, v235
	v_mul_f32_e32 v241, v228, v228
	v_fmac_f32_e32 v241, v229, v229
	v_fmac_f32_e32 v241, v230, v230
	v_fmac_f32_e32 v241, v231, v231
	v_lshlrev_b32_e32 v228, 16, v148
	v_and_b32_e32 v229, 0xffff0000, v148
	v_lshlrev_b32_e32 v230, 16, v149
	v_and_b32_e32 v231, 0xffff0000, v149
	v_fmac_f32_e32 v228, s23, v128
	v_fmac_f32_e32 v229, s23, v124
	v_fmac_f32_e32 v230, s23, v120
	v_fmac_f32_e32 v231, s23, v116
	v_cvt_pk_bf16_f32 v236, v228, v229
	v_cvt_pk_bf16_f32 v237, v230, v231
	global_store_dwordx2 v[246:247], v[236:237], off offset:0
	v_lshlrev_b32_e32 v228, 16, v236
	v_and_b32_e32 v229, 0xffff0000, v236
	v_lshlrev_b32_e32 v230, 16, v237
	v_and_b32_e32 v231, 0xffff0000, v237
	v_mul_f32_e32 v242, v228, v228
	v_fmac_f32_e32 v242, v229, v229
	v_fmac_f32_e32 v242, v230, v230
	v_fmac_f32_e32 v242, v231, v231
	v_lshlrev_b32_e32 v228, 16, v150
	v_and_b32_e32 v229, 0xffff0000, v150
	v_lshlrev_b32_e32 v230, 16, v151
	v_and_b32_e32 v231, 0xffff0000, v151
	v_fmac_f32_e32 v228, s23, v129
	v_fmac_f32_e32 v229, s23, v125
	v_fmac_f32_e32 v230, s23, v121
	v_fmac_f32_e32 v231, s23, v117
	v_cvt_pk_bf16_f32 v238, v228, v229
	v_cvt_pk_bf16_f32 v239, v230, v231
	global_store_dwordx2 v[246:247], v[238:239], off offset:2048
	v_lshlrev_b32_e32 v228, 16, v238
	v_and_b32_e32 v229, 0xffff0000, v238
	v_lshlrev_b32_e32 v230, 16, v239
	v_and_b32_e32 v231, 0xffff0000, v239
	v_mul_f32_e32 v243, v228, v228
	v_fmac_f32_e32 v243, v229, v229
	v_fmac_f32_e32 v243, v230, v230
	v_fmac_f32_e32 v243, v231, v231
	v_lshl_add_u64 v[246:247], v[246:247], 0, s[92:93]
	v_add_f32_dpp v240, v240, v240 quad_perm:[1,0,3,2] row_mask:0xf bank_mask:0xf bound_ctrl:1
	v_add_f32_dpp v241, v241, v241 quad_perm:[1,0,3,2] row_mask:0xf bank_mask:0xf bound_ctrl:1
	v_add_f32_dpp v242, v242, v242 quad_perm:[1,0,3,2] row_mask:0xf bank_mask:0xf bound_ctrl:1
	v_add_f32_dpp v243, v243, v243 quad_perm:[1,0,3,2] row_mask:0xf bank_mask:0xf bound_ctrl:1
	v_add_f32_dpp v240, v240, v240 quad_perm:[2,3,0,1] row_mask:0xf bank_mask:0xf bound_ctrl:1
	v_add_f32_dpp v241, v241, v241 quad_perm:[2,3,0,1] row_mask:0xf bank_mask:0xf bound_ctrl:1
	v_add_f32_dpp v242, v242, v242 quad_perm:[2,3,0,1] row_mask:0xf bank_mask:0xf bound_ctrl:1
	v_add_f32_dpp v243, v243, v243 quad_perm:[2,3,0,1] row_mask:0xf bank_mask:0xf bound_ctrl:1
	v_add_f32_dpp v240, v240, v240 row_half_mirror row_mask:0xf bank_mask:0xf bound_ctrl:1
	v_add_f32_dpp v241, v241, v241 row_half_mirror row_mask:0xf bank_mask:0xf bound_ctrl:1
	v_add_f32_dpp v242, v242, v242 row_half_mirror row_mask:0xf bank_mask:0xf bound_ctrl:1
	v_add_f32_dpp v243, v243, v243 row_half_mirror row_mask:0xf bank_mask:0xf bound_ctrl:1
	v_add_f32_dpp v240, v240, v240 row_mirror row_mask:0xf bank_mask:0xf bound_ctrl:1
	v_add_f32_dpp v241, v241, v241 row_mirror row_mask:0xf bank_mask:0xf bound_ctrl:1
	v_add_f32_dpp v242, v242, v242 row_mirror row_mask:0xf bank_mask:0xf bound_ctrl:1
	v_add_f32_dpp v243, v243, v243 row_mirror row_mask:0xf bank_mask:0xf bound_ctrl:1
	v_cndmask_b32_e32 v244, v240, v241, vcc
	v_cndmask_b32_e64 v244, v244, v242, s[14:15]
	v_cndmask_b32_e64 v244, v244, v243, s[20:21]
	global_store_dword v[250:251], v244, off offset:0
	s_waitcnt vmcnt(13)
	v_lshlrev_b32_e32 v228, 16, v152
	v_and_b32_e32 v229, 0xffff0000, v152
	v_lshlrev_b32_e32 v230, 16, v153
	v_and_b32_e32 v231, 0xffff0000, v153
	v_fmac_f32_e32 v228, s23, v110
	v_fmac_f32_e32 v229, s23, v106
	v_fmac_f32_e32 v230, s23, v102
	v_fmac_f32_e32 v231, s23, v98
	v_cvt_pk_bf16_f32 v232, v228, v229
	v_cvt_pk_bf16_f32 v233, v230, v231
	global_store_dwordx2 v[246:247], v[232:233], off offset:-4096
	v_lshlrev_b32_e32 v228, 16, v232
	v_and_b32_e32 v229, 0xffff0000, v232
	v_lshlrev_b32_e32 v230, 16, v233
	v_and_b32_e32 v231, 0xffff0000, v233
	v_mul_f32_e32 v240, v228, v228
	v_fmac_f32_e32 v240, v229, v229
	v_fmac_f32_e32 v240, v230, v230
	v_fmac_f32_e32 v240, v231, v231
	v_lshlrev_b32_e32 v228, 16, v154
	v_and_b32_e32 v229, 0xffff0000, v154
	v_lshlrev_b32_e32 v230, 16, v155
	v_and_b32_e32 v231, 0xffff0000, v155
	v_fmac_f32_e32 v228, s23, v111
	v_fmac_f32_e32 v229, s23, v107
	v_fmac_f32_e32 v230, s23, v103
	v_fmac_f32_e32 v231, s23, v99
	v_cvt_pk_bf16_f32 v234, v228, v229
	v_cvt_pk_bf16_f32 v235, v230, v231
	global_store_dwordx2 v[246:247], v[234:235], off offset:-2048
	v_lshlrev_b32_e32 v228, 16, v234
	v_and_b32_e32 v229, 0xffff0000, v234
	v_lshlrev_b32_e32 v230, 16, v235
	v_and_b32_e32 v231, 0xffff0000, v235
	v_mul_f32_e32 v241, v228, v228
	v_fmac_f32_e32 v241, v229, v229
	v_fmac_f32_e32 v241, v230, v230
	v_fmac_f32_e32 v241, v231, v231
	v_lshlrev_b32_e32 v228, 16, v156
	v_and_b32_e32 v229, 0xffff0000, v156
	v_lshlrev_b32_e32 v230, 16, v157
	v_and_b32_e32 v231, 0xffff0000, v157
	v_fmac_f32_e32 v228, s23, v112
	v_fmac_f32_e32 v229, s23, v108
	v_fmac_f32_e32 v230, s23, v104
	v_fmac_f32_e32 v231, s23, v100
	v_cvt_pk_bf16_f32 v236, v228, v229
	v_cvt_pk_bf16_f32 v237, v230, v231
	global_store_dwordx2 v[246:247], v[236:237], off offset:0
	v_lshlrev_b32_e32 v228, 16, v236
	v_and_b32_e32 v229, 0xffff0000, v236
	v_lshlrev_b32_e32 v230, 16, v237
	v_and_b32_e32 v231, 0xffff0000, v237
	v_mul_f32_e32 v242, v228, v228
	v_fmac_f32_e32 v242, v229, v229
	v_fmac_f32_e32 v242, v230, v230
	v_fmac_f32_e32 v242, v231, v231
	v_lshlrev_b32_e32 v228, 16, v158
	v_and_b32_e32 v229, 0xffff0000, v158
	v_lshlrev_b32_e32 v230, 16, v159
	v_and_b32_e32 v231, 0xffff0000, v159
	v_fmac_f32_e32 v228, s23, v113
	v_fmac_f32_e32 v229, s23, v109
	v_fmac_f32_e32 v230, s23, v105
	v_fmac_f32_e32 v231, s23, v101
	v_cvt_pk_bf16_f32 v238, v228, v229
	v_cvt_pk_bf16_f32 v239, v230, v231
	global_store_dwordx2 v[246:247], v[238:239], off offset:2048
	v_lshlrev_b32_e32 v228, 16, v238
	v_and_b32_e32 v229, 0xffff0000, v238
	v_lshlrev_b32_e32 v230, 16, v239
	v_and_b32_e32 v231, 0xffff0000, v239
	v_mul_f32_e32 v243, v228, v228
	v_fmac_f32_e32 v243, v229, v229
	v_fmac_f32_e32 v243, v230, v230
	v_fmac_f32_e32 v243, v231, v231
	v_lshl_add_u64 v[246:247], v[246:247], 0, s[92:93]
	v_add_f32_dpp v240, v240, v240 quad_perm:[1,0,3,2] row_mask:0xf bank_mask:0xf bound_ctrl:1
	v_add_f32_dpp v241, v241, v241 quad_perm:[1,0,3,2] row_mask:0xf bank_mask:0xf bound_ctrl:1
	v_add_f32_dpp v242, v242, v242 quad_perm:[1,0,3,2] row_mask:0xf bank_mask:0xf bound_ctrl:1
	v_add_f32_dpp v243, v243, v243 quad_perm:[1,0,3,2] row_mask:0xf bank_mask:0xf bound_ctrl:1
	v_add_f32_dpp v240, v240, v240 quad_perm:[2,3,0,1] row_mask:0xf bank_mask:0xf bound_ctrl:1
	v_add_f32_dpp v241, v241, v241 quad_perm:[2,3,0,1] row_mask:0xf bank_mask:0xf bound_ctrl:1
	v_add_f32_dpp v242, v242, v242 quad_perm:[2,3,0,1] row_mask:0xf bank_mask:0xf bound_ctrl:1
	v_add_f32_dpp v243, v243, v243 quad_perm:[2,3,0,1] row_mask:0xf bank_mask:0xf bound_ctrl:1
	v_add_f32_dpp v240, v240, v240 row_half_mirror row_mask:0xf bank_mask:0xf bound_ctrl:1
	v_add_f32_dpp v241, v241, v241 row_half_mirror row_mask:0xf bank_mask:0xf bound_ctrl:1
	v_add_f32_dpp v242, v242, v242 row_half_mirror row_mask:0xf bank_mask:0xf bound_ctrl:1
	v_add_f32_dpp v243, v243, v243 row_half_mirror row_mask:0xf bank_mask:0xf bound_ctrl:1
	v_add_f32_dpp v240, v240, v240 row_mirror row_mask:0xf bank_mask:0xf bound_ctrl:1
	v_add_f32_dpp v241, v241, v241 row_mirror row_mask:0xf bank_mask:0xf bound_ctrl:1
	v_add_f32_dpp v242, v242, v242 row_mirror row_mask:0xf bank_mask:0xf bound_ctrl:1
	v_add_f32_dpp v243, v243, v243 row_mirror row_mask:0xf bank_mask:0xf bound_ctrl:1
	v_cndmask_b32_e32 v244, v240, v241, vcc
	v_cndmask_b32_e64 v244, v244, v242, s[14:15]
	v_cndmask_b32_e64 v244, v244, v243, s[20:21]
	global_store_dword v[250:251], v244, off offset:1024
	global_load_dwordx2 v[126:127], v[252:253], off offset:-4096
	global_load_dwordx2 v[128:129], v[252:253], off offset:-2048
	global_load_dwordx2 v[122:123], v[252:253], off offset:0
	global_load_dwordx2 v[124:125], v[252:253], off offset:2048
	v_lshl_add_u64 v[252:253], v[252:253], 0, s[92:93]
	global_load_dwordx2 v[118:119], v[252:253], off offset:-4096
	global_load_dwordx2 v[120:121], v[252:253], off offset:-2048
	global_load_dwordx2 v[114:115], v[252:253], off offset:0
	global_load_dwordx2 v[116:117], v[252:253], off offset:2048
	v_lshl_add_u64 v[252:253], v[252:253], 0, s[92:93]
	global_load_dwordx2 v[110:111], v[252:253], off offset:-4096
	global_load_dwordx2 v[112:113], v[252:253], off offset:-2048
	global_load_dwordx2 v[106:107], v[252:253], off offset:0
	global_load_dwordx2 v[108:109], v[252:253], off offset:2048
	v_lshl_add_u64 v[252:253], v[252:253], 0, s[92:93]
	global_load_dwordx2 v[102:103], v[252:253], off offset:-4096
	global_load_dwordx2 v[104:105], v[252:253], off offset:-2048
	global_load_dwordx2 v[98:99], v[252:253], off offset:0
	global_load_dwordx2 v[100:101], v[252:253], off offset:2048
	v_lshl_add_u64 v[252:253], v[252:253], 0, s[92:93]
	s_waitcnt vmcnt(30)
	v_lshlrev_b32_e32 v228, 16, v160
	v_and_b32_e32 v229, 0xffff0000, v160
	v_lshlrev_b32_e32 v230, 16, v161
	v_and_b32_e32 v231, 0xffff0000, v161
	v_fmac_f32_e32 v228, s23, v94
	v_fmac_f32_e32 v229, s23, v90
	v_fmac_f32_e32 v230, s23, v86
	v_fmac_f32_e32 v231, s23, v82
	v_cvt_pk_bf16_f32 v232, v228, v229
	v_cvt_pk_bf16_f32 v233, v230, v231
	global_store_dwordx2 v[246:247], v[232:233], off offset:-4096
	v_lshlrev_b32_e32 v228, 16, v232
	v_and_b32_e32 v229, 0xffff0000, v232
	v_lshlrev_b32_e32 v230, 16, v233
	v_and_b32_e32 v231, 0xffff0000, v233
	v_mul_f32_e32 v240, v228, v228
	v_fmac_f32_e32 v240, v229, v229
	v_fmac_f32_e32 v240, v230, v230
	v_fmac_f32_e32 v240, v231, v231
	v_lshlrev_b32_e32 v228, 16, v162
	v_and_b32_e32 v229, 0xffff0000, v162
	v_lshlrev_b32_e32 v230, 16, v163
	v_and_b32_e32 v231, 0xffff0000, v163
	v_fmac_f32_e32 v228, s23, v95
	v_fmac_f32_e32 v229, s23, v91
	v_fmac_f32_e32 v230, s23, v87
	v_fmac_f32_e32 v231, s23, v83
	v_cvt_pk_bf16_f32 v234, v228, v229
	v_cvt_pk_bf16_f32 v235, v230, v231
	global_store_dwordx2 v[246:247], v[234:235], off offset:-2048
	v_lshlrev_b32_e32 v228, 16, v234
	v_and_b32_e32 v229, 0xffff0000, v234
	v_lshlrev_b32_e32 v230, 16, v235
	v_and_b32_e32 v231, 0xffff0000, v235
	v_mul_f32_e32 v241, v228, v228
	v_fmac_f32_e32 v241, v229, v229
	v_fmac_f32_e32 v241, v230, v230
	v_fmac_f32_e32 v241, v231, v231
	v_lshlrev_b32_e32 v228, 16, v164
	v_and_b32_e32 v229, 0xffff0000, v164
	v_lshlrev_b32_e32 v230, 16, v165
	v_and_b32_e32 v231, 0xffff0000, v165
	v_fmac_f32_e32 v228, s23, v96
	v_fmac_f32_e32 v229, s23, v92
	v_fmac_f32_e32 v230, s23, v88
	v_fmac_f32_e32 v231, s23, v84
	v_cvt_pk_bf16_f32 v236, v228, v229
	v_cvt_pk_bf16_f32 v237, v230, v231
	global_store_dwordx2 v[246:247], v[236:237], off offset:0
	v_lshlrev_b32_e32 v228, 16, v236
	v_and_b32_e32 v229, 0xffff0000, v236
	v_lshlrev_b32_e32 v230, 16, v237
	v_and_b32_e32 v231, 0xffff0000, v237
	v_mul_f32_e32 v242, v228, v228
	v_fmac_f32_e32 v242, v229, v229
	v_fmac_f32_e32 v242, v230, v230
	v_fmac_f32_e32 v242, v231, v231
	v_lshlrev_b32_e32 v228, 16, v166
	v_and_b32_e32 v229, 0xffff0000, v166
	v_lshlrev_b32_e32 v230, 16, v167
	v_and_b32_e32 v231, 0xffff0000, v167
	v_fmac_f32_e32 v228, s23, v97
	v_fmac_f32_e32 v229, s23, v93
	v_fmac_f32_e32 v230, s23, v89
	v_fmac_f32_e32 v231, s23, v85
	v_cvt_pk_bf16_f32 v238, v228, v229
	v_cvt_pk_bf16_f32 v239, v230, v231
	global_store_dwordx2 v[246:247], v[238:239], off offset:2048
	v_lshlrev_b32_e32 v228, 16, v238
	v_and_b32_e32 v229, 0xffff0000, v238
	v_lshlrev_b32_e32 v230, 16, v239
	v_and_b32_e32 v231, 0xffff0000, v239
	v_mul_f32_e32 v243, v228, v228
	v_fmac_f32_e32 v243, v229, v229
	v_fmac_f32_e32 v243, v230, v230
	v_fmac_f32_e32 v243, v231, v231
	v_lshl_add_u64 v[246:247], v[246:247], 0, s[92:93]
	v_add_f32_dpp v240, v240, v240 quad_perm:[1,0,3,2] row_mask:0xf bank_mask:0xf bound_ctrl:1
	v_add_f32_dpp v241, v241, v241 quad_perm:[1,0,3,2] row_mask:0xf bank_mask:0xf bound_ctrl:1
	v_add_f32_dpp v242, v242, v242 quad_perm:[1,0,3,2] row_mask:0xf bank_mask:0xf bound_ctrl:1
	v_add_f32_dpp v243, v243, v243 quad_perm:[1,0,3,2] row_mask:0xf bank_mask:0xf bound_ctrl:1
	v_add_f32_dpp v240, v240, v240 quad_perm:[2,3,0,1] row_mask:0xf bank_mask:0xf bound_ctrl:1
	v_add_f32_dpp v241, v241, v241 quad_perm:[2,3,0,1] row_mask:0xf bank_mask:0xf bound_ctrl:1
	v_add_f32_dpp v242, v242, v242 quad_perm:[2,3,0,1] row_mask:0xf bank_mask:0xf bound_ctrl:1
	v_add_f32_dpp v243, v243, v243 quad_perm:[2,3,0,1] row_mask:0xf bank_mask:0xf bound_ctrl:1
	v_add_f32_dpp v240, v240, v240 row_half_mirror row_mask:0xf bank_mask:0xf bound_ctrl:1
	v_add_f32_dpp v241, v241, v241 row_half_mirror row_mask:0xf bank_mask:0xf bound_ctrl:1
	v_add_f32_dpp v242, v242, v242 row_half_mirror row_mask:0xf bank_mask:0xf bound_ctrl:1
	v_add_f32_dpp v243, v243, v243 row_half_mirror row_mask:0xf bank_mask:0xf bound_ctrl:1
	v_add_f32_dpp v240, v240, v240 row_mirror row_mask:0xf bank_mask:0xf bound_ctrl:1
	v_add_f32_dpp v241, v241, v241 row_mirror row_mask:0xf bank_mask:0xf bound_ctrl:1
	v_add_f32_dpp v242, v242, v242 row_mirror row_mask:0xf bank_mask:0xf bound_ctrl:1
	v_add_f32_dpp v243, v243, v243 row_mirror row_mask:0xf bank_mask:0xf bound_ctrl:1
	v_cndmask_b32_e32 v244, v240, v241, vcc
	v_cndmask_b32_e64 v244, v244, v242, s[14:15]
	v_cndmask_b32_e64 v244, v244, v243, s[20:21]
	global_store_dword v[250:251], v244, off offset:2048
	s_waitcnt vmcnt(31)
	v_lshlrev_b32_e32 v228, 16, v168
	v_and_b32_e32 v229, 0xffff0000, v168
	v_lshlrev_b32_e32 v230, 16, v169
	v_and_b32_e32 v231, 0xffff0000, v169
	v_fmac_f32_e32 v228, s23, v78
	v_fmac_f32_e32 v229, s23, v74
	v_fmac_f32_e32 v230, s23, v70
	v_fmac_f32_e32 v231, s23, v66
	v_cvt_pk_bf16_f32 v232, v228, v229
	v_cvt_pk_bf16_f32 v233, v230, v231
	global_store_dwordx2 v[246:247], v[232:233], off offset:-4096
	v_lshlrev_b32_e32 v228, 16, v232
	v_and_b32_e32 v229, 0xffff0000, v232
	v_lshlrev_b32_e32 v230, 16, v233
	v_and_b32_e32 v231, 0xffff0000, v233
	v_mul_f32_e32 v240, v228, v228
	v_fmac_f32_e32 v240, v229, v229
	v_fmac_f32_e32 v240, v230, v230
	v_fmac_f32_e32 v240, v231, v231
	v_lshlrev_b32_e32 v228, 16, v170
	v_and_b32_e32 v229, 0xffff0000, v170
	v_lshlrev_b32_e32 v230, 16, v171
	v_and_b32_e32 v231, 0xffff0000, v171
	v_fmac_f32_e32 v228, s23, v79
	v_fmac_f32_e32 v229, s23, v75
	v_fmac_f32_e32 v230, s23, v71
	v_fmac_f32_e32 v231, s23, v67
	v_cvt_pk_bf16_f32 v234, v228, v229
	v_cvt_pk_bf16_f32 v235, v230, v231
	global_store_dwordx2 v[246:247], v[234:235], off offset:-2048
	v_lshlrev_b32_e32 v228, 16, v234
	v_and_b32_e32 v229, 0xffff0000, v234
	v_lshlrev_b32_e32 v230, 16, v235
	v_and_b32_e32 v231, 0xffff0000, v235
	v_mul_f32_e32 v241, v228, v228
	v_fmac_f32_e32 v241, v229, v229
	v_fmac_f32_e32 v241, v230, v230
	v_fmac_f32_e32 v241, v231, v231
	v_lshlrev_b32_e32 v228, 16, v172
	v_and_b32_e32 v229, 0xffff0000, v172
	v_lshlrev_b32_e32 v230, 16, v173
	v_and_b32_e32 v231, 0xffff0000, v173
	v_fmac_f32_e32 v228, s23, v80
	v_fmac_f32_e32 v229, s23, v76
	v_fmac_f32_e32 v230, s23, v72
	v_fmac_f32_e32 v231, s23, v68
	v_cvt_pk_bf16_f32 v236, v228, v229
	v_cvt_pk_bf16_f32 v237, v230, v231
	global_store_dwordx2 v[246:247], v[236:237], off offset:0
	v_lshlrev_b32_e32 v228, 16, v236
	v_and_b32_e32 v229, 0xffff0000, v236
	v_lshlrev_b32_e32 v230, 16, v237
	v_and_b32_e32 v231, 0xffff0000, v237
	v_mul_f32_e32 v242, v228, v228
	v_fmac_f32_e32 v242, v229, v229
	v_fmac_f32_e32 v242, v230, v230
	v_fmac_f32_e32 v242, v231, v231
	v_lshlrev_b32_e32 v228, 16, v174
	v_and_b32_e32 v229, 0xffff0000, v174
	v_lshlrev_b32_e32 v230, 16, v175
	v_and_b32_e32 v231, 0xffff0000, v175
	v_fmac_f32_e32 v228, s23, v81
	v_fmac_f32_e32 v229, s23, v77
	v_fmac_f32_e32 v230, s23, v73
	v_fmac_f32_e32 v231, s23, v69
	v_cvt_pk_bf16_f32 v238, v228, v229
	v_cvt_pk_bf16_f32 v239, v230, v231
	global_store_dwordx2 v[246:247], v[238:239], off offset:2048
	v_lshlrev_b32_e32 v228, 16, v238
	v_and_b32_e32 v229, 0xffff0000, v238
	v_lshlrev_b32_e32 v230, 16, v239
	v_and_b32_e32 v231, 0xffff0000, v239
	v_mul_f32_e32 v243, v228, v228
	v_fmac_f32_e32 v243, v229, v229
	v_fmac_f32_e32 v243, v230, v230
	v_fmac_f32_e32 v243, v231, v231
	v_lshl_add_u64 v[246:247], v[246:247], 0, s[92:93]
	v_add_f32_dpp v240, v240, v240 quad_perm:[1,0,3,2] row_mask:0xf bank_mask:0xf bound_ctrl:1
	v_add_f32_dpp v241, v241, v241 quad_perm:[1,0,3,2] row_mask:0xf bank_mask:0xf bound_ctrl:1
	v_add_f32_dpp v242, v242, v242 quad_perm:[1,0,3,2] row_mask:0xf bank_mask:0xf bound_ctrl:1
	v_add_f32_dpp v243, v243, v243 quad_perm:[1,0,3,2] row_mask:0xf bank_mask:0xf bound_ctrl:1
	v_add_f32_dpp v240, v240, v240 quad_perm:[2,3,0,1] row_mask:0xf bank_mask:0xf bound_ctrl:1
	v_add_f32_dpp v241, v241, v241 quad_perm:[2,3,0,1] row_mask:0xf bank_mask:0xf bound_ctrl:1
	v_add_f32_dpp v242, v242, v242 quad_perm:[2,3,0,1] row_mask:0xf bank_mask:0xf bound_ctrl:1
	v_add_f32_dpp v243, v243, v243 quad_perm:[2,3,0,1] row_mask:0xf bank_mask:0xf bound_ctrl:1
	v_add_f32_dpp v240, v240, v240 row_half_mirror row_mask:0xf bank_mask:0xf bound_ctrl:1
	v_add_f32_dpp v241, v241, v241 row_half_mirror row_mask:0xf bank_mask:0xf bound_ctrl:1
	v_add_f32_dpp v242, v242, v242 row_half_mirror row_mask:0xf bank_mask:0xf bound_ctrl:1
	v_add_f32_dpp v243, v243, v243 row_half_mirror row_mask:0xf bank_mask:0xf bound_ctrl:1
	v_add_f32_dpp v240, v240, v240 row_mirror row_mask:0xf bank_mask:0xf bound_ctrl:1
	v_add_f32_dpp v241, v241, v241 row_mirror row_mask:0xf bank_mask:0xf bound_ctrl:1
	v_add_f32_dpp v242, v242, v242 row_mirror row_mask:0xf bank_mask:0xf bound_ctrl:1
	v_add_f32_dpp v243, v243, v243 row_mirror row_mask:0xf bank_mask:0xf bound_ctrl:1
	v_cndmask_b32_e32 v244, v240, v241, vcc
	v_cndmask_b32_e64 v244, v244, v242, s[14:15]
	v_cndmask_b32_e64 v244, v244, v243, s[20:21]
	global_store_dword v[250:251], v244, off offset:3072
	s_waitcnt vmcnt(22)
	v_lshlrev_b32_e32 v228, 16, v126
	v_and_b32_e32 v229, 0xffff0000, v126
	v_lshlrev_b32_e32 v230, 16, v127
	v_and_b32_e32 v231, 0xffff0000, v127
	v_fmac_f32_e32 v228, s23, v62
	v_fmac_f32_e32 v229, s23, v58
	v_fmac_f32_e32 v230, s23, v54
	v_fmac_f32_e32 v231, s23, v50
	v_cvt_pk_bf16_f32 v232, v228, v229
	v_cvt_pk_bf16_f32 v233, v230, v231
	global_store_dwordx2 v[246:247], v[232:233], off offset:-4096
	v_lshlrev_b32_e32 v228, 16, v232
	v_and_b32_e32 v229, 0xffff0000, v232
	v_lshlrev_b32_e32 v230, 16, v233
	v_and_b32_e32 v231, 0xffff0000, v233
	v_mul_f32_e32 v240, v228, v228
	v_fmac_f32_e32 v240, v229, v229
	v_fmac_f32_e32 v240, v230, v230
	v_fmac_f32_e32 v240, v231, v231
	v_lshlrev_b32_e32 v228, 16, v128
	v_and_b32_e32 v229, 0xffff0000, v128
	v_lshlrev_b32_e32 v230, 16, v129
	v_and_b32_e32 v231, 0xffff0000, v129
	v_fmac_f32_e32 v228, s23, v63
	v_fmac_f32_e32 v229, s23, v59
	v_fmac_f32_e32 v230, s23, v55
	v_fmac_f32_e32 v231, s23, v51
	v_cvt_pk_bf16_f32 v234, v228, v229
	v_cvt_pk_bf16_f32 v235, v230, v231
	global_store_dwordx2 v[246:247], v[234:235], off offset:-2048
	v_lshlrev_b32_e32 v228, 16, v234
	v_and_b32_e32 v229, 0xffff0000, v234
	v_lshlrev_b32_e32 v230, 16, v235
	v_and_b32_e32 v231, 0xffff0000, v235
	v_mul_f32_e32 v241, v228, v228
	v_fmac_f32_e32 v241, v229, v229
	v_fmac_f32_e32 v241, v230, v230
	v_fmac_f32_e32 v241, v231, v231
	v_lshlrev_b32_e32 v228, 16, v122
	v_and_b32_e32 v229, 0xffff0000, v122
	v_lshlrev_b32_e32 v230, 16, v123
	v_and_b32_e32 v231, 0xffff0000, v123
	v_fmac_f32_e32 v228, s23, v64
	v_fmac_f32_e32 v229, s23, v60
	v_fmac_f32_e32 v230, s23, v56
	v_fmac_f32_e32 v231, s23, v52
	v_cvt_pk_bf16_f32 v236, v228, v229
	v_cvt_pk_bf16_f32 v237, v230, v231
	global_store_dwordx2 v[246:247], v[236:237], off offset:0
	v_lshlrev_b32_e32 v228, 16, v236
	v_and_b32_e32 v229, 0xffff0000, v236
	v_lshlrev_b32_e32 v230, 16, v237
	v_and_b32_e32 v231, 0xffff0000, v237
	v_mul_f32_e32 v242, v228, v228
	v_fmac_f32_e32 v242, v229, v229
	v_fmac_f32_e32 v242, v230, v230
	v_fmac_f32_e32 v242, v231, v231
	v_lshlrev_b32_e32 v228, 16, v124
	v_and_b32_e32 v229, 0xffff0000, v124
	v_lshlrev_b32_e32 v230, 16, v125
	v_and_b32_e32 v231, 0xffff0000, v125
	v_fmac_f32_e32 v228, s23, v65
	v_fmac_f32_e32 v229, s23, v61
	v_fmac_f32_e32 v230, s23, v57
	v_fmac_f32_e32 v231, s23, v53
	v_cvt_pk_bf16_f32 v238, v228, v229
	v_cvt_pk_bf16_f32 v239, v230, v231
	global_store_dwordx2 v[246:247], v[238:239], off offset:2048
	v_lshlrev_b32_e32 v228, 16, v238
	v_and_b32_e32 v229, 0xffff0000, v238
	v_lshlrev_b32_e32 v230, 16, v239
	v_and_b32_e32 v231, 0xffff0000, v239
	v_mul_f32_e32 v243, v228, v228
	v_fmac_f32_e32 v243, v229, v229
	v_fmac_f32_e32 v243, v230, v230
	v_fmac_f32_e32 v243, v231, v231
	v_lshl_add_u64 v[246:247], v[246:247], 0, s[92:93]
	v_add_f32_dpp v240, v240, v240 quad_perm:[1,0,3,2] row_mask:0xf bank_mask:0xf bound_ctrl:1
	v_add_f32_dpp v241, v241, v241 quad_perm:[1,0,3,2] row_mask:0xf bank_mask:0xf bound_ctrl:1
	v_add_f32_dpp v242, v242, v242 quad_perm:[1,0,3,2] row_mask:0xf bank_mask:0xf bound_ctrl:1
	v_add_f32_dpp v243, v243, v243 quad_perm:[1,0,3,2] row_mask:0xf bank_mask:0xf bound_ctrl:1
	v_add_f32_dpp v240, v240, v240 quad_perm:[2,3,0,1] row_mask:0xf bank_mask:0xf bound_ctrl:1
	v_add_f32_dpp v241, v241, v241 quad_perm:[2,3,0,1] row_mask:0xf bank_mask:0xf bound_ctrl:1
	v_add_f32_dpp v242, v242, v242 quad_perm:[2,3,0,1] row_mask:0xf bank_mask:0xf bound_ctrl:1
	v_add_f32_dpp v243, v243, v243 quad_perm:[2,3,0,1] row_mask:0xf bank_mask:0xf bound_ctrl:1
	v_add_f32_dpp v240, v240, v240 row_half_mirror row_mask:0xf bank_mask:0xf bound_ctrl:1
	v_add_f32_dpp v241, v241, v241 row_half_mirror row_mask:0xf bank_mask:0xf bound_ctrl:1
	v_add_f32_dpp v242, v242, v242 row_half_mirror row_mask:0xf bank_mask:0xf bound_ctrl:1
	v_add_f32_dpp v243, v243, v243 row_half_mirror row_mask:0xf bank_mask:0xf bound_ctrl:1
	v_add_f32_dpp v240, v240, v240 row_mirror row_mask:0xf bank_mask:0xf bound_ctrl:1
	v_add_f32_dpp v241, v241, v241 row_mirror row_mask:0xf bank_mask:0xf bound_ctrl:1
	v_add_f32_dpp v242, v242, v242 row_mirror row_mask:0xf bank_mask:0xf bound_ctrl:1
	v_add_f32_dpp v243, v243, v243 row_mirror row_mask:0xf bank_mask:0xf bound_ctrl:1
	v_cndmask_b32_e32 v244, v240, v241, vcc
	v_cndmask_b32_e64 v244, v244, v242, s[14:15]
	v_cndmask_b32_e64 v244, v244, v243, s[20:21]
	v_mov_b32_e32 v254, 0x1000
	v_lshl_add_u64 v[250:251], v[250:251], 0, v[254:255]
	global_store_dword v[250:251], v244, off offset:0
	s_waitcnt vmcnt(23)
	v_lshlrev_b32_e32 v228, 16, v118
	v_and_b32_e32 v229, 0xffff0000, v118
	v_lshlrev_b32_e32 v230, 16, v119
	v_and_b32_e32 v231, 0xffff0000, v119
	v_fmac_f32_e32 v228, s23, v46
	v_fmac_f32_e32 v229, s23, v42
	v_fmac_f32_e32 v230, s23, v38
	v_fmac_f32_e32 v231, s23, v34
	v_cvt_pk_bf16_f32 v232, v228, v229
	v_cvt_pk_bf16_f32 v233, v230, v231
	global_store_dwordx2 v[246:247], v[232:233], off offset:-4096
	v_lshlrev_b32_e32 v228, 16, v232
	v_and_b32_e32 v229, 0xffff0000, v232
	v_lshlrev_b32_e32 v230, 16, v233
	v_and_b32_e32 v231, 0xffff0000, v233
	v_mul_f32_e32 v240, v228, v228
	v_fmac_f32_e32 v240, v229, v229
	v_fmac_f32_e32 v240, v230, v230
	v_fmac_f32_e32 v240, v231, v231
	v_lshlrev_b32_e32 v228, 16, v120
	v_and_b32_e32 v229, 0xffff0000, v120
	v_lshlrev_b32_e32 v230, 16, v121
	v_and_b32_e32 v231, 0xffff0000, v121
	v_fmac_f32_e32 v228, s23, v47
	v_fmac_f32_e32 v229, s23, v43
	v_fmac_f32_e32 v230, s23, v39
	v_fmac_f32_e32 v231, s23, v35
	v_cvt_pk_bf16_f32 v234, v228, v229
	v_cvt_pk_bf16_f32 v235, v230, v231
	global_store_dwordx2 v[246:247], v[234:235], off offset:-2048
	v_lshlrev_b32_e32 v228, 16, v234
	v_and_b32_e32 v229, 0xffff0000, v234
	v_lshlrev_b32_e32 v230, 16, v235
	v_and_b32_e32 v231, 0xffff0000, v235
	v_mul_f32_e32 v241, v228, v228
	v_fmac_f32_e32 v241, v229, v229
	v_fmac_f32_e32 v241, v230, v230
	v_fmac_f32_e32 v241, v231, v231
	v_lshlrev_b32_e32 v228, 16, v114
	v_and_b32_e32 v229, 0xffff0000, v114
	v_lshlrev_b32_e32 v230, 16, v115
	v_and_b32_e32 v231, 0xffff0000, v115
	v_fmac_f32_e32 v228, s23, v48
	v_fmac_f32_e32 v229, s23, v44
	v_fmac_f32_e32 v230, s23, v40
	v_fmac_f32_e32 v231, s23, v36
	v_cvt_pk_bf16_f32 v236, v228, v229
	v_cvt_pk_bf16_f32 v237, v230, v231
	global_store_dwordx2 v[246:247], v[236:237], off offset:0
	v_lshlrev_b32_e32 v228, 16, v236
	v_and_b32_e32 v229, 0xffff0000, v236
	v_lshlrev_b32_e32 v230, 16, v237
	v_and_b32_e32 v231, 0xffff0000, v237
	v_mul_f32_e32 v242, v228, v228
	v_fmac_f32_e32 v242, v229, v229
	v_fmac_f32_e32 v242, v230, v230
	v_fmac_f32_e32 v242, v231, v231
	v_lshlrev_b32_e32 v228, 16, v116
	v_and_b32_e32 v229, 0xffff0000, v116
	v_lshlrev_b32_e32 v230, 16, v117
	v_and_b32_e32 v231, 0xffff0000, v117
	v_fmac_f32_e32 v228, s23, v49
	v_fmac_f32_e32 v229, s23, v45
	v_fmac_f32_e32 v230, s23, v41
	v_fmac_f32_e32 v231, s23, v37
	v_cvt_pk_bf16_f32 v238, v228, v229
	v_cvt_pk_bf16_f32 v239, v230, v231
	global_store_dwordx2 v[246:247], v[238:239], off offset:2048
	v_lshlrev_b32_e32 v228, 16, v238
	v_and_b32_e32 v229, 0xffff0000, v238
	v_lshlrev_b32_e32 v230, 16, v239
	v_and_b32_e32 v231, 0xffff0000, v239
	v_mul_f32_e32 v243, v228, v228
	v_fmac_f32_e32 v243, v229, v229
	v_fmac_f32_e32 v243, v230, v230
	v_fmac_f32_e32 v243, v231, v231
	v_lshl_add_u64 v[246:247], v[246:247], 0, s[92:93]
	v_add_f32_dpp v240, v240, v240 quad_perm:[1,0,3,2] row_mask:0xf bank_mask:0xf bound_ctrl:1
	v_add_f32_dpp v241, v241, v241 quad_perm:[1,0,3,2] row_mask:0xf bank_mask:0xf bound_ctrl:1
	v_add_f32_dpp v242, v242, v242 quad_perm:[1,0,3,2] row_mask:0xf bank_mask:0xf bound_ctrl:1
	v_add_f32_dpp v243, v243, v243 quad_perm:[1,0,3,2] row_mask:0xf bank_mask:0xf bound_ctrl:1
	v_add_f32_dpp v240, v240, v240 quad_perm:[2,3,0,1] row_mask:0xf bank_mask:0xf bound_ctrl:1
	v_add_f32_dpp v241, v241, v241 quad_perm:[2,3,0,1] row_mask:0xf bank_mask:0xf bound_ctrl:1
	v_add_f32_dpp v242, v242, v242 quad_perm:[2,3,0,1] row_mask:0xf bank_mask:0xf bound_ctrl:1
	v_add_f32_dpp v243, v243, v243 quad_perm:[2,3,0,1] row_mask:0xf bank_mask:0xf bound_ctrl:1
	v_add_f32_dpp v240, v240, v240 row_half_mirror row_mask:0xf bank_mask:0xf bound_ctrl:1
	v_add_f32_dpp v241, v241, v241 row_half_mirror row_mask:0xf bank_mask:0xf bound_ctrl:1
	v_add_f32_dpp v242, v242, v242 row_half_mirror row_mask:0xf bank_mask:0xf bound_ctrl:1
	v_add_f32_dpp v243, v243, v243 row_half_mirror row_mask:0xf bank_mask:0xf bound_ctrl:1
	v_add_f32_dpp v240, v240, v240 row_mirror row_mask:0xf bank_mask:0xf bound_ctrl:1
	v_add_f32_dpp v241, v241, v241 row_mirror row_mask:0xf bank_mask:0xf bound_ctrl:1
	v_add_f32_dpp v242, v242, v242 row_mirror row_mask:0xf bank_mask:0xf bound_ctrl:1
	v_add_f32_dpp v243, v243, v243 row_mirror row_mask:0xf bank_mask:0xf bound_ctrl:1
	v_cndmask_b32_e32 v244, v240, v241, vcc
	v_cndmask_b32_e64 v244, v244, v242, s[14:15]
	v_cndmask_b32_e64 v244, v244, v243, s[20:21]
	global_store_dword v[250:251], v244, off offset:1024
	s_waitcnt vmcnt(24)
	v_lshlrev_b32_e32 v228, 16, v110
	v_and_b32_e32 v229, 0xffff0000, v110
	v_lshlrev_b32_e32 v230, 16, v111
	v_and_b32_e32 v231, 0xffff0000, v111
	v_fmac_f32_e32 v228, s23, v30
	v_fmac_f32_e32 v229, s23, v26
	v_fmac_f32_e32 v230, s23, v22
	v_fmac_f32_e32 v231, s23, v18
	v_cvt_pk_bf16_f32 v232, v228, v229
	v_cvt_pk_bf16_f32 v233, v230, v231
	global_store_dwordx2 v[246:247], v[232:233], off offset:-4096
	v_lshlrev_b32_e32 v228, 16, v232
	v_and_b32_e32 v229, 0xffff0000, v232
	v_lshlrev_b32_e32 v230, 16, v233
	v_and_b32_e32 v231, 0xffff0000, v233
	v_mul_f32_e32 v240, v228, v228
	v_fmac_f32_e32 v240, v229, v229
	v_fmac_f32_e32 v240, v230, v230
	v_fmac_f32_e32 v240, v231, v231
	v_lshlrev_b32_e32 v228, 16, v112
	v_and_b32_e32 v229, 0xffff0000, v112
	v_lshlrev_b32_e32 v230, 16, v113
	v_and_b32_e32 v231, 0xffff0000, v113
	v_fmac_f32_e32 v228, s23, v31
	v_fmac_f32_e32 v229, s23, v27
	v_fmac_f32_e32 v230, s23, v23
	v_fmac_f32_e32 v231, s23, v19
	v_cvt_pk_bf16_f32 v234, v228, v229
	v_cvt_pk_bf16_f32 v235, v230, v231
	global_store_dwordx2 v[246:247], v[234:235], off offset:-2048
	v_lshlrev_b32_e32 v228, 16, v234
	v_and_b32_e32 v229, 0xffff0000, v234
	v_lshlrev_b32_e32 v230, 16, v235
	v_and_b32_e32 v231, 0xffff0000, v235
	v_mul_f32_e32 v241, v228, v228
	v_fmac_f32_e32 v241, v229, v229
	v_fmac_f32_e32 v241, v230, v230
	v_fmac_f32_e32 v241, v231, v231
	v_lshlrev_b32_e32 v228, 16, v106
	v_and_b32_e32 v229, 0xffff0000, v106
	v_lshlrev_b32_e32 v230, 16, v107
	v_and_b32_e32 v231, 0xffff0000, v107
	v_fmac_f32_e32 v228, s23, v32
	v_fmac_f32_e32 v229, s23, v28
	v_fmac_f32_e32 v230, s23, v24
	v_fmac_f32_e32 v231, s23, v20
	v_cvt_pk_bf16_f32 v236, v228, v229
	v_cvt_pk_bf16_f32 v237, v230, v231
	global_store_dwordx2 v[246:247], v[236:237], off offset:0
	v_lshlrev_b32_e32 v228, 16, v236
	v_and_b32_e32 v229, 0xffff0000, v236
	v_lshlrev_b32_e32 v230, 16, v237
	v_and_b32_e32 v231, 0xffff0000, v237
	v_mul_f32_e32 v242, v228, v228
	v_fmac_f32_e32 v242, v229, v229
	v_fmac_f32_e32 v242, v230, v230
	v_fmac_f32_e32 v242, v231, v231
	v_lshlrev_b32_e32 v228, 16, v108
	v_and_b32_e32 v229, 0xffff0000, v108
	v_lshlrev_b32_e32 v230, 16, v109
	v_and_b32_e32 v231, 0xffff0000, v109
	v_fmac_f32_e32 v228, s23, v33
	v_fmac_f32_e32 v229, s23, v29
	v_fmac_f32_e32 v230, s23, v25
	v_fmac_f32_e32 v231, s23, v21
	v_cvt_pk_bf16_f32 v238, v228, v229
	v_cvt_pk_bf16_f32 v239, v230, v231
	global_store_dwordx2 v[246:247], v[238:239], off offset:2048
	v_lshlrev_b32_e32 v228, 16, v238
	v_and_b32_e32 v229, 0xffff0000, v238
	v_lshlrev_b32_e32 v230, 16, v239
	v_and_b32_e32 v231, 0xffff0000, v239
	v_mul_f32_e32 v243, v228, v228
	v_fmac_f32_e32 v243, v229, v229
	v_fmac_f32_e32 v243, v230, v230
	v_fmac_f32_e32 v243, v231, v231
	v_lshl_add_u64 v[246:247], v[246:247], 0, s[92:93]
	v_add_f32_dpp v240, v240, v240 quad_perm:[1,0,3,2] row_mask:0xf bank_mask:0xf bound_ctrl:1
	v_add_f32_dpp v241, v241, v241 quad_perm:[1,0,3,2] row_mask:0xf bank_mask:0xf bound_ctrl:1
	v_add_f32_dpp v242, v242, v242 quad_perm:[1,0,3,2] row_mask:0xf bank_mask:0xf bound_ctrl:1
	v_add_f32_dpp v243, v243, v243 quad_perm:[1,0,3,2] row_mask:0xf bank_mask:0xf bound_ctrl:1
	v_add_f32_dpp v240, v240, v240 quad_perm:[2,3,0,1] row_mask:0xf bank_mask:0xf bound_ctrl:1
	v_add_f32_dpp v241, v241, v241 quad_perm:[2,3,0,1] row_mask:0xf bank_mask:0xf bound_ctrl:1
	v_add_f32_dpp v242, v242, v242 quad_perm:[2,3,0,1] row_mask:0xf bank_mask:0xf bound_ctrl:1
	v_add_f32_dpp v243, v243, v243 quad_perm:[2,3,0,1] row_mask:0xf bank_mask:0xf bound_ctrl:1
	v_add_f32_dpp v240, v240, v240 row_half_mirror row_mask:0xf bank_mask:0xf bound_ctrl:1
	v_add_f32_dpp v241, v241, v241 row_half_mirror row_mask:0xf bank_mask:0xf bound_ctrl:1
	v_add_f32_dpp v242, v242, v242 row_half_mirror row_mask:0xf bank_mask:0xf bound_ctrl:1
	v_add_f32_dpp v243, v243, v243 row_half_mirror row_mask:0xf bank_mask:0xf bound_ctrl:1
	v_add_f32_dpp v240, v240, v240 row_mirror row_mask:0xf bank_mask:0xf bound_ctrl:1
	v_add_f32_dpp v241, v241, v241 row_mirror row_mask:0xf bank_mask:0xf bound_ctrl:1
	v_add_f32_dpp v242, v242, v242 row_mirror row_mask:0xf bank_mask:0xf bound_ctrl:1
	v_add_f32_dpp v243, v243, v243 row_mirror row_mask:0xf bank_mask:0xf bound_ctrl:1
	v_cndmask_b32_e32 v244, v240, v241, vcc
	v_cndmask_b32_e64 v244, v244, v242, s[14:15]
	v_cndmask_b32_e64 v244, v244, v243, s[20:21]
	global_store_dword v[250:251], v244, off offset:2048
	s_waitcnt vmcnt(25)
	v_lshlrev_b32_e32 v228, 16, v102
	v_and_b32_e32 v229, 0xffff0000, v102
	v_lshlrev_b32_e32 v230, 16, v103
	v_and_b32_e32 v231, 0xffff0000, v103
	v_fmac_f32_e32 v228, s23, v14
	v_fmac_f32_e32 v229, s23, v10
	v_fmac_f32_e32 v230, s23, v6
	v_fmac_f32_e32 v231, s23, v2
	v_cvt_pk_bf16_f32 v232, v228, v229
	v_cvt_pk_bf16_f32 v233, v230, v231
	global_store_dwordx2 v[246:247], v[232:233], off offset:-4096
	v_lshlrev_b32_e32 v228, 16, v232
	v_and_b32_e32 v229, 0xffff0000, v232
	v_lshlrev_b32_e32 v230, 16, v233
	v_and_b32_e32 v231, 0xffff0000, v233
	v_mul_f32_e32 v240, v228, v228
	v_fmac_f32_e32 v240, v229, v229
	v_fmac_f32_e32 v240, v230, v230
	v_fmac_f32_e32 v240, v231, v231
	v_lshlrev_b32_e32 v228, 16, v104
	v_and_b32_e32 v229, 0xffff0000, v104
	v_lshlrev_b32_e32 v230, 16, v105
	v_and_b32_e32 v231, 0xffff0000, v105
	v_fmac_f32_e32 v228, s23, v15
	v_fmac_f32_e32 v229, s23, v11
	v_fmac_f32_e32 v230, s23, v7
	v_fmac_f32_e32 v231, s23, v3
	v_cvt_pk_bf16_f32 v234, v228, v229
	v_cvt_pk_bf16_f32 v235, v230, v231
	global_store_dwordx2 v[246:247], v[234:235], off offset:-2048
	v_lshlrev_b32_e32 v228, 16, v234
	v_and_b32_e32 v229, 0xffff0000, v234
	v_lshlrev_b32_e32 v230, 16, v235
	v_and_b32_e32 v231, 0xffff0000, v235
	v_mul_f32_e32 v241, v228, v228
	v_fmac_f32_e32 v241, v229, v229
	v_fmac_f32_e32 v241, v230, v230
	v_fmac_f32_e32 v241, v231, v231
	v_lshlrev_b32_e32 v228, 16, v98
	v_and_b32_e32 v229, 0xffff0000, v98
	v_lshlrev_b32_e32 v230, 16, v99
	v_and_b32_e32 v231, 0xffff0000, v99
	v_fmac_f32_e32 v228, s23, v16
	v_fmac_f32_e32 v229, s23, v12
	v_fmac_f32_e32 v230, s23, v8
	v_fmac_f32_e32 v231, s23, v4
	v_cvt_pk_bf16_f32 v236, v228, v229
	v_cvt_pk_bf16_f32 v237, v230, v231
	global_store_dwordx2 v[246:247], v[236:237], off offset:0
	v_lshlrev_b32_e32 v228, 16, v236
	v_and_b32_e32 v229, 0xffff0000, v236
	v_lshlrev_b32_e32 v230, 16, v237
	v_and_b32_e32 v231, 0xffff0000, v237
	v_mul_f32_e32 v242, v228, v228
	v_fmac_f32_e32 v242, v229, v229
	v_fmac_f32_e32 v242, v230, v230
	v_fmac_f32_e32 v242, v231, v231
	v_lshlrev_b32_e32 v228, 16, v100
	v_and_b32_e32 v229, 0xffff0000, v100
	v_lshlrev_b32_e32 v230, 16, v101
	v_and_b32_e32 v231, 0xffff0000, v101
	v_fmac_f32_e32 v228, s23, v17
	v_fmac_f32_e32 v229, s23, v13
	v_fmac_f32_e32 v230, s23, v9
	v_fmac_f32_e32 v231, s23, v5
	v_cvt_pk_bf16_f32 v238, v228, v229
	v_cvt_pk_bf16_f32 v239, v230, v231
	global_store_dwordx2 v[246:247], v[238:239], off offset:2048
	v_lshlrev_b32_e32 v228, 16, v238
	v_and_b32_e32 v229, 0xffff0000, v238
	v_lshlrev_b32_e32 v230, 16, v239
	v_and_b32_e32 v231, 0xffff0000, v239
	v_mul_f32_e32 v243, v228, v228
	v_fmac_f32_e32 v243, v229, v229
	v_fmac_f32_e32 v243, v230, v230
	v_fmac_f32_e32 v243, v231, v231
	v_lshl_add_u64 v[246:247], v[246:247], 0, s[92:93]
	v_add_f32_dpp v240, v240, v240 quad_perm:[1,0,3,2] row_mask:0xf bank_mask:0xf bound_ctrl:1
	v_add_f32_dpp v241, v241, v241 quad_perm:[1,0,3,2] row_mask:0xf bank_mask:0xf bound_ctrl:1
	v_add_f32_dpp v242, v242, v242 quad_perm:[1,0,3,2] row_mask:0xf bank_mask:0xf bound_ctrl:1
	v_add_f32_dpp v243, v243, v243 quad_perm:[1,0,3,2] row_mask:0xf bank_mask:0xf bound_ctrl:1
	v_add_f32_dpp v240, v240, v240 quad_perm:[2,3,0,1] row_mask:0xf bank_mask:0xf bound_ctrl:1
	v_add_f32_dpp v241, v241, v241 quad_perm:[2,3,0,1] row_mask:0xf bank_mask:0xf bound_ctrl:1
	v_add_f32_dpp v242, v242, v242 quad_perm:[2,3,0,1] row_mask:0xf bank_mask:0xf bound_ctrl:1
	v_add_f32_dpp v243, v243, v243 quad_perm:[2,3,0,1] row_mask:0xf bank_mask:0xf bound_ctrl:1
	v_add_f32_dpp v240, v240, v240 row_half_mirror row_mask:0xf bank_mask:0xf bound_ctrl:1
	v_add_f32_dpp v241, v241, v241 row_half_mirror row_mask:0xf bank_mask:0xf bound_ctrl:1
	v_add_f32_dpp v242, v242, v242 row_half_mirror row_mask:0xf bank_mask:0xf bound_ctrl:1
	v_add_f32_dpp v243, v243, v243 row_half_mirror row_mask:0xf bank_mask:0xf bound_ctrl:1
	v_add_f32_dpp v240, v240, v240 row_mirror row_mask:0xf bank_mask:0xf bound_ctrl:1
	v_add_f32_dpp v241, v241, v241 row_mirror row_mask:0xf bank_mask:0xf bound_ctrl:1
	v_add_f32_dpp v242, v242, v242 row_mirror row_mask:0xf bank_mask:0xf bound_ctrl:1
	v_add_f32_dpp v243, v243, v243 row_mirror row_mask:0xf bank_mask:0xf bound_ctrl:1
	v_cndmask_b32_e32 v244, v240, v241, vcc
	v_cndmask_b32_e64 v244, v244, v242, s[14:15]
	v_cndmask_b32_e64 v244, v244, v243, s[20:21]
	global_store_dword v[250:251], v244, off offset:3072
	s_branch .LBB0_289
.Lresid_f32:
	v_mul_u32_u24_e32 v254, 12, v130
	v_mov_b32_e32 v255, 0
	v_lshl_add_u64 v[250:251], v[134:135], 0, v[254:255]
	s_movk_i32 s14, 0x1000
	s_mov_b32 s15, 0
	s_mov_b32 s20, 0xd000
	s_mov_b32 s21, 0
	global_load_dwordx2 v[144:145], v[252:253], off offset:-4096
	global_load_dwordx2 v[146:147], v[252:253], off offset:-2048
	global_load_dwordx2 v[148:149], v[252:253], off offset:0
	global_load_dwordx2 v[150:151], v[252:253], off offset:2048
	v_lshl_add_u64 v[252:253], v[252:253], 0, s[92:93]
	global_load_dwordx2 v[152:153], v[252:253], off offset:-4096
	global_load_dwordx2 v[154:155], v[252:253], off offset:-2048
	global_load_dwordx2 v[156:157], v[252:253], off offset:0
	global_load_dwordx2 v[158:159], v[252:253], off offset:2048
	v_lshl_add_u64 v[252:253], v[252:253], 0, s[92:93]
	global_load_dwordx2 v[160:161], v[252:253], off offset:-4096
	global_load_dwordx2 v[162:163], v[252:253], off offset:-2048
	global_load_dwordx2 v[164:165], v[252:253], off offset:0
	global_load_dwordx2 v[166:167], v[252:253], off offset:2048
	v_lshl_add_u64 v[252:253], v[252:253], 0, s[92:93]
	global_load_dwordx2 v[168:169], v[252:253], off offset:-4096
	global_load_dwordx2 v[170:171], v[252:253], off offset:-2048
	global_load_dwordx2 v[172:173], v[252:253], off offset:0
	global_load_dwordx2 v[174:175], v[252:253], off offset:2048
	v_lshl_add_u64 v[252:253], v[252:253], 0, s[92:93]
	s_waitcnt vmcnt(12)
	v_lshlrev_b32_e32 v228, 16, v144
	v_and_b32_e32 v229, 0xffff0000, v144
	v_lshlrev_b32_e32 v230, 16, v145
	v_and_b32_e32 v231, 0xffff0000, v145
	v_fmac_f32_e32 v228, s23, v126
	v_fmac_f32_e32 v229, s23, v122
	v_fmac_f32_e32 v230, s23, v118
	v_fmac_f32_e32 v231, s23, v114
	global_store_dwordx4 v[250:251], v[228:231], off
	v_lshl_add_u64 v[250:251], v[250:251], 0, s[14:15]
	v_lshlrev_b32_e32 v232, 16, v146
	v_and_b32_e32 v233, 0xffff0000, v146
	v_lshlrev_b32_e32 v234, 16, v147
	v_and_b32_e32 v235, 0xffff0000, v147
	v_fmac_f32_e32 v232, s23, v127
	v_fmac_f32_e32 v233, s23, v123
	v_fmac_f32_e32 v234, s23, v119
	v_fmac_f32_e32 v235, s23, v115
	global_store_dwordx4 v[250:251], v[232:235], off
	v_lshl_add_u64 v[250:251], v[250:251], 0, s[14:15]
	v_lshlrev_b32_e32 v236, 16, v148
	v_and_b32_e32 v237, 0xffff0000, v148
	v_lshlrev_b32_e32 v238, 16, v149
	v_and_b32_e32 v239, 0xffff0000, v149
	v_fmac_f32_e32 v236, s23, v128
	v_fmac_f32_e32 v237, s23, v124
	v_fmac_f32_e32 v238, s23, v120
	v_fmac_f32_e32 v239, s23, v116
	global_store_dwordx4 v[250:251], v[236:239], off
	v_lshl_add_u64 v[250:251], v[250:251], 0, s[14:15]
	v_lshlrev_b32_e32 v240, 16, v150
	v_and_b32_e32 v241, 0xffff0000, v150
	v_lshlrev_b32_e32 v242, 16, v151
	v_and_b32_e32 v243, 0xffff0000, v151
	v_fmac_f32_e32 v240, s23, v129
	v_fmac_f32_e32 v241, s23, v125
	v_fmac_f32_e32 v242, s23, v121
	v_fmac_f32_e32 v243, s23, v117
	global_store_dwordx4 v[250:251], v[240:243], off
	v_lshl_add_u64 v[250:251], v[250:251], 0, s[20:21]
	s_waitcnt vmcnt(12)
	v_lshlrev_b32_e32 v228, 16, v152
	v_and_b32_e32 v229, 0xffff0000, v152
	v_lshlrev_b32_e32 v230, 16, v153
	v_and_b32_e32 v231, 0xffff0000, v153
	v_fmac_f32_e32 v228, s23, v110
	v_fmac_f32_e32 v229, s23, v106
	v_fmac_f32_e32 v230, s23, v102
	v_fmac_f32_e32 v231, s23, v98
	global_store_dwordx4 v[250:251], v[228:231], off
	v_lshl_add_u64 v[250:251], v[250:251], 0, s[14:15]
	v_lshlrev_b32_e32 v232, 16, v154
	v_and_b32_e32 v233, 0xffff0000, v154
	v_lshlrev_b32_e32 v234, 16, v155
	v_and_b32_e32 v235, 0xffff0000, v155
	v_fmac_f32_e32 v232, s23, v111
	v_fmac_f32_e32 v233, s23, v107
	v_fmac_f32_e32 v234, s23, v103
	v_fmac_f32_e32 v235, s23, v99
	global_store_dwordx4 v[250:251], v[232:235], off
	v_lshl_add_u64 v[250:251], v[250:251], 0, s[14:15]
	v_lshlrev_b32_e32 v236, 16, v156
	v_and_b32_e32 v237, 0xffff0000, v156
	v_lshlrev_b32_e32 v238, 16, v157
	v_and_b32_e32 v239, 0xffff0000, v157
	v_fmac_f32_e32 v236, s23, v112
	v_fmac_f32_e32 v237, s23, v108
	v_fmac_f32_e32 v238, s23, v104
	v_fmac_f32_e32 v239, s23, v100
	global_store_dwordx4 v[250:251], v[236:239], off
	v_lshl_add_u64 v[250:251], v[250:251], 0, s[14:15]
	v_lshlrev_b32_e32 v240, 16, v158
	v_and_b32_e32 v241, 0xffff0000, v158
	v_lshlrev_b32_e32 v242, 16, v159
	v_and_b32_e32 v243, 0xffff0000, v159
	v_fmac_f32_e32 v240, s23, v113
	v_fmac_f32_e32 v241, s23, v109
	v_fmac_f32_e32 v242, s23, v105
	v_fmac_f32_e32 v243, s23, v101
	global_store_dwordx4 v[250:251], v[240:243], off
	v_lshl_add_u64 v[250:251], v[250:251], 0, s[20:21]
	global_load_dwordx2 v[126:127], v[252:253], off offset:-4096
	global_load_dwordx2 v[128:129], v[252:253], off offset:-2048
	global_load_dwordx2 v[122:123], v[252:253], off offset:0
	global_load_dwordx2 v[124:125], v[252:253], off offset:2048
	v_lshl_add_u64 v[252:253], v[252:253], 0, s[92:93]
	global_load_dwordx2 v[118:119], v[252:253], off offset:-4096
	global_load_dwordx2 v[120:121], v[252:253], off offset:-2048
	global_load_dwordx2 v[114:115], v[252:253], off offset:0
	global_load_dwordx2 v[116:117], v[252:253], off offset:2048
	v_lshl_add_u64 v[252:253], v[252:253], 0, s[92:93]
	global_load_dwordx2 v[110:111], v[252:253], off offset:-4096
	global_load_dwordx2 v[112:113], v[252:253], off offset:-2048
	global_load_dwordx2 v[106:107], v[252:253], off offset:0
	global_load_dwordx2 v[108:109], v[252:253], off offset:2048
	v_lshl_add_u64 v[252:253], v[252:253], 0, s[92:93]
	global_load_dwordx2 v[102:103], v[252:253], off offset:-4096
	global_load_dwordx2 v[104:105], v[252:253], off offset:-2048
	global_load_dwordx2 v[98:99], v[252:253], off offset:0
	global_load_dwordx2 v[100:101], v[252:253], off offset:2048
	v_lshl_add_u64 v[252:253], v[252:253], 0, s[92:93]
	s_waitcnt vmcnt(28)
	v_lshlrev_b32_e32 v228, 16, v160
	v_and_b32_e32 v229, 0xffff0000, v160
	v_lshlrev_b32_e32 v230, 16, v161
	v_and_b32_e32 v231, 0xffff0000, v161
	v_fmac_f32_e32 v228, s23, v94
	v_fmac_f32_e32 v229, s23, v90
	v_fmac_f32_e32 v230, s23, v86
	v_fmac_f32_e32 v231, s23, v82
	global_store_dwordx4 v[250:251], v[228:231], off
	v_lshl_add_u64 v[250:251], v[250:251], 0, s[14:15]
	v_lshlrev_b32_e32 v232, 16, v162
	v_and_b32_e32 v233, 0xffff0000, v162
	v_lshlrev_b32_e32 v234, 16, v163
	v_and_b32_e32 v235, 0xffff0000, v163
	v_fmac_f32_e32 v232, s23, v95
	v_fmac_f32_e32 v233, s23, v91
	v_fmac_f32_e32 v234, s23, v87
	v_fmac_f32_e32 v235, s23, v83
	global_store_dwordx4 v[250:251], v[232:235], off
	v_lshl_add_u64 v[250:251], v[250:251], 0, s[14:15]
	v_lshlrev_b32_e32 v236, 16, v164
	v_and_b32_e32 v237, 0xffff0000, v164
	v_lshlrev_b32_e32 v238, 16, v165
	v_and_b32_e32 v239, 0xffff0000, v165
	v_fmac_f32_e32 v236, s23, v96
	v_fmac_f32_e32 v237, s23, v92
	v_fmac_f32_e32 v238, s23, v88
	v_fmac_f32_e32 v239, s23, v84
	global_store_dwordx4 v[250:251], v[236:239], off
	v_lshl_add_u64 v[250:251], v[250:251], 0, s[14:15]
	v_lshlrev_b32_e32 v240, 16, v166
	v_and_b32_e32 v241, 0xffff0000, v166
	v_lshlrev_b32_e32 v242, 16, v167
	v_and_b32_e32 v243, 0xffff0000, v167
	v_fmac_f32_e32 v240, s23, v97
	v_fmac_f32_e32 v241, s23, v93
	v_fmac_f32_e32 v242, s23, v89
	v_fmac_f32_e32 v243, s23, v85
	global_store_dwordx4 v[250:251], v[240:243], off
	v_lshl_add_u64 v[250:251], v[250:251], 0, s[20:21]
	s_waitcnt vmcnt(28)
	v_lshlrev_b32_e32 v228, 16, v168
	v_and_b32_e32 v229, 0xffff0000, v168
	v_lshlrev_b32_e32 v230, 16, v169
	v_and_b32_e32 v231, 0xffff0000, v169
	v_fmac_f32_e32 v228, s23, v78
	v_fmac_f32_e32 v229, s23, v74
	v_fmac_f32_e32 v230, s23, v70
	v_fmac_f32_e32 v231, s23, v66
	global_store_dwordx4 v[250:251], v[228:231], off
	v_lshl_add_u64 v[250:251], v[250:251], 0, s[14:15]
	v_lshlrev_b32_e32 v232, 16, v170
	v_and_b32_e32 v233, 0xffff0000, v170
	v_lshlrev_b32_e32 v234, 16, v171
	v_and_b32_e32 v235, 0xffff0000, v171
	v_fmac_f32_e32 v232, s23, v79
	v_fmac_f32_e32 v233, s23, v75
	v_fmac_f32_e32 v234, s23, v71
	v_fmac_f32_e32 v235, s23, v67
	global_store_dwordx4 v[250:251], v[232:235], off
	v_lshl_add_u64 v[250:251], v[250:251], 0, s[14:15]
	v_lshlrev_b32_e32 v236, 16, v172
	v_and_b32_e32 v237, 0xffff0000, v172
	v_lshlrev_b32_e32 v238, 16, v173
	v_and_b32_e32 v239, 0xffff0000, v173
	v_fmac_f32_e32 v236, s23, v80
	v_fmac_f32_e32 v237, s23, v76
	v_fmac_f32_e32 v238, s23, v72
	v_fmac_f32_e32 v239, s23, v68
	global_store_dwordx4 v[250:251], v[236:239], off
	v_lshl_add_u64 v[250:251], v[250:251], 0, s[14:15]
	v_lshlrev_b32_e32 v240, 16, v174
	v_and_b32_e32 v241, 0xffff0000, v174
	v_lshlrev_b32_e32 v242, 16, v175
	v_and_b32_e32 v243, 0xffff0000, v175
	v_fmac_f32_e32 v240, s23, v81
	v_fmac_f32_e32 v241, s23, v77
	v_fmac_f32_e32 v242, s23, v73
	v_fmac_f32_e32 v243, s23, v69
	global_store_dwordx4 v[250:251], v[240:243], off
	v_lshl_add_u64 v[250:251], v[250:251], 0, s[20:21]
	s_waitcnt vmcnt(20)
	v_lshlrev_b32_e32 v228, 16, v126
	v_and_b32_e32 v229, 0xffff0000, v126
	v_lshlrev_b32_e32 v230, 16, v127
	v_and_b32_e32 v231, 0xffff0000, v127
	v_fmac_f32_e32 v228, s23, v62
	v_fmac_f32_e32 v229, s23, v58
	v_fmac_f32_e32 v230, s23, v54
	v_fmac_f32_e32 v231, s23, v50
	global_store_dwordx4 v[250:251], v[228:231], off
	v_lshl_add_u64 v[250:251], v[250:251], 0, s[14:15]
	v_lshlrev_b32_e32 v232, 16, v128
	v_and_b32_e32 v233, 0xffff0000, v128
	v_lshlrev_b32_e32 v234, 16, v129
	v_and_b32_e32 v235, 0xffff0000, v129
	v_fmac_f32_e32 v232, s23, v63
	v_fmac_f32_e32 v233, s23, v59
	v_fmac_f32_e32 v234, s23, v55
	v_fmac_f32_e32 v235, s23, v51
	global_store_dwordx4 v[250:251], v[232:235], off
	v_lshl_add_u64 v[250:251], v[250:251], 0, s[14:15]
	v_lshlrev_b32_e32 v236, 16, v122
	v_and_b32_e32 v237, 0xffff0000, v122
	v_lshlrev_b32_e32 v238, 16, v123
	v_and_b32_e32 v239, 0xffff0000, v123
	v_fmac_f32_e32 v236, s23, v64
	v_fmac_f32_e32 v237, s23, v60
	v_fmac_f32_e32 v238, s23, v56
	v_fmac_f32_e32 v239, s23, v52
	global_store_dwordx4 v[250:251], v[236:239], off
	v_lshl_add_u64 v[250:251], v[250:251], 0, s[14:15]
	v_lshlrev_b32_e32 v240, 16, v124
	v_and_b32_e32 v241, 0xffff0000, v124
	v_lshlrev_b32_e32 v242, 16, v125
	v_and_b32_e32 v243, 0xffff0000, v125
	v_fmac_f32_e32 v240, s23, v65
	v_fmac_f32_e32 v241, s23, v61
	v_fmac_f32_e32 v242, s23, v57
	v_fmac_f32_e32 v243, s23, v53
	global_store_dwordx4 v[250:251], v[240:243], off
	v_lshl_add_u64 v[250:251], v[250:251], 0, s[20:21]
	s_waitcnt vmcnt(20)
	v_lshlrev_b32_e32 v228, 16, v118
	v_and_b32_e32 v229, 0xffff0000, v118
	v_lshlrev_b32_e32 v230, 16, v119
	v_and_b32_e32 v231, 0xffff0000, v119
	v_fmac_f32_e32 v228, s23, v46
	v_fmac_f32_e32 v229, s23, v42
	v_fmac_f32_e32 v230, s23, v38
	v_fmac_f32_e32 v231, s23, v34
	global_store_dwordx4 v[250:251], v[228:231], off
	v_lshl_add_u64 v[250:251], v[250:251], 0, s[14:15]
	v_lshlrev_b32_e32 v232, 16, v120
	v_and_b32_e32 v233, 0xffff0000, v120
	v_lshlrev_b32_e32 v234, 16, v121
	v_and_b32_e32 v235, 0xffff0000, v121
	v_fmac_f32_e32 v232, s23, v47
	v_fmac_f32_e32 v233, s23, v43
	v_fmac_f32_e32 v234, s23, v39
	v_fmac_f32_e32 v235, s23, v35
	global_store_dwordx4 v[250:251], v[232:235], off
	v_lshl_add_u64 v[250:251], v[250:251], 0, s[14:15]
	v_lshlrev_b32_e32 v236, 16, v114
	v_and_b32_e32 v237, 0xffff0000, v114
	v_lshlrev_b32_e32 v238, 16, v115
	v_and_b32_e32 v239, 0xffff0000, v115
	v_fmac_f32_e32 v236, s23, v48
	v_fmac_f32_e32 v237, s23, v44
	v_fmac_f32_e32 v238, s23, v40
	v_fmac_f32_e32 v239, s23, v36
	global_store_dwordx4 v[250:251], v[236:239], off
	v_lshl_add_u64 v[250:251], v[250:251], 0, s[14:15]
	v_lshlrev_b32_e32 v240, 16, v116
	v_and_b32_e32 v241, 0xffff0000, v116
	v_lshlrev_b32_e32 v242, 16, v117
	v_and_b32_e32 v243, 0xffff0000, v117
	v_fmac_f32_e32 v240, s23, v49
	v_fmac_f32_e32 v241, s23, v45
	v_fmac_f32_e32 v242, s23, v41
	v_fmac_f32_e32 v243, s23, v37
	global_store_dwordx4 v[250:251], v[240:243], off
	v_lshl_add_u64 v[250:251], v[250:251], 0, s[20:21]
	s_waitcnt vmcnt(20)
	v_lshlrev_b32_e32 v228, 16, v110
	v_and_b32_e32 v229, 0xffff0000, v110
	v_lshlrev_b32_e32 v230, 16, v111
	v_and_b32_e32 v231, 0xffff0000, v111
	v_fmac_f32_e32 v228, s23, v30
	v_fmac_f32_e32 v229, s23, v26
	v_fmac_f32_e32 v230, s23, v22
	v_fmac_f32_e32 v231, s23, v18
	global_store_dwordx4 v[250:251], v[228:231], off
	v_lshl_add_u64 v[250:251], v[250:251], 0, s[14:15]
	v_lshlrev_b32_e32 v232, 16, v112
	v_and_b32_e32 v233, 0xffff0000, v112
	v_lshlrev_b32_e32 v234, 16, v113
	v_and_b32_e32 v235, 0xffff0000, v113
	v_fmac_f32_e32 v232, s23, v31
	v_fmac_f32_e32 v233, s23, v27
	v_fmac_f32_e32 v234, s23, v23
	v_fmac_f32_e32 v235, s23, v19
	global_store_dwordx4 v[250:251], v[232:235], off
	v_lshl_add_u64 v[250:251], v[250:251], 0, s[14:15]
	v_lshlrev_b32_e32 v236, 16, v106
	v_and_b32_e32 v237, 0xffff0000, v106
	v_lshlrev_b32_e32 v238, 16, v107
	v_and_b32_e32 v239, 0xffff0000, v107
	v_fmac_f32_e32 v236, s23, v32
	v_fmac_f32_e32 v237, s23, v28
	v_fmac_f32_e32 v238, s23, v24
	v_fmac_f32_e32 v239, s23, v20
	global_store_dwordx4 v[250:251], v[236:239], off
	v_lshl_add_u64 v[250:251], v[250:251], 0, s[14:15]
	v_lshlrev_b32_e32 v240, 16, v108
	v_and_b32_e32 v241, 0xffff0000, v108
	v_lshlrev_b32_e32 v242, 16, v109
	v_and_b32_e32 v243, 0xffff0000, v109
	v_fmac_f32_e32 v240, s23, v33
	v_fmac_f32_e32 v241, s23, v29
	v_fmac_f32_e32 v242, s23, v25
	v_fmac_f32_e32 v243, s23, v21
	global_store_dwordx4 v[250:251], v[240:243], off
	v_lshl_add_u64 v[250:251], v[250:251], 0, s[20:21]
	s_waitcnt vmcnt(20)
	v_lshlrev_b32_e32 v228, 16, v102
	v_and_b32_e32 v229, 0xffff0000, v102
	v_lshlrev_b32_e32 v230, 16, v103
	v_and_b32_e32 v231, 0xffff0000, v103
	v_fmac_f32_e32 v228, s23, v14
	v_fmac_f32_e32 v229, s23, v10
	v_fmac_f32_e32 v230, s23, v6
	v_fmac_f32_e32 v231, s23, v2
	global_store_dwordx4 v[250:251], v[228:231], off
	v_lshl_add_u64 v[250:251], v[250:251], 0, s[14:15]
	v_lshlrev_b32_e32 v232, 16, v104
	v_and_b32_e32 v233, 0xffff0000, v104
	v_lshlrev_b32_e32 v234, 16, v105
	v_and_b32_e32 v235, 0xffff0000, v105
	v_fmac_f32_e32 v232, s23, v15
	v_fmac_f32_e32 v233, s23, v11
	v_fmac_f32_e32 v234, s23, v7
	v_fmac_f32_e32 v235, s23, v3
	global_store_dwordx4 v[250:251], v[232:235], off
	v_lshl_add_u64 v[250:251], v[250:251], 0, s[14:15]
	v_lshlrev_b32_e32 v236, 16, v98
	v_and_b32_e32 v237, 0xffff0000, v98
	v_lshlrev_b32_e32 v238, 16, v99
	v_and_b32_e32 v239, 0xffff0000, v99
	v_fmac_f32_e32 v236, s23, v16
	v_fmac_f32_e32 v237, s23, v12
	v_fmac_f32_e32 v238, s23, v8
	v_fmac_f32_e32 v239, s23, v4
	global_store_dwordx4 v[250:251], v[236:239], off
	v_lshl_add_u64 v[250:251], v[250:251], 0, s[14:15]
	v_lshlrev_b32_e32 v240, 16, v100
	v_and_b32_e32 v241, 0xffff0000, v100
	v_lshlrev_b32_e32 v242, 16, v101
	v_and_b32_e32 v243, 0xffff0000, v101
	v_fmac_f32_e32 v240, s23, v17
	v_fmac_f32_e32 v241, s23, v13
	v_fmac_f32_e32 v242, s23, v9
	v_fmac_f32_e32 v243, s23, v5
	global_store_dwordx4 v[250:251], v[240:243], off
	v_lshl_add_u64 v[250:251], v[250:251], 0, s[20:21]
	s_branch .LBB0_289
.LBB0_416:
	v_readlane_b32 s68, v227, 47
	s_andn2_b64 vcc, exec, s[16:17]
	v_readlane_b32 s69, v227, 48
	s_movk_i32 s40, 0xac0
	s_mov_b64 s[44:45], 0x10200
	s_cbranch_vccnz .LBB0_725
	s_load_dwordx2 s[16:17], s[0:1], 0x0
	v_readlane_b32 s8, v227, 55
	s_cmp_lt_i32 s8, 1
	s_mov_b64 s[6:7], -1
	v_readlane_b32 s9, v227, 56
	v_readlane_b32 s10, v227, 57
	v_readlane_b32 s11, v227, 58
	s_cbranch_scc1 .LBB0_672
	v_readlane_b32 s8, v227, 55
	s_cmp_gt_i32 s8, 1
	v_readlane_b32 s9, v227, 56
	v_readlane_b32 s10, v227, 57
	v_readlane_b32 s11, v227, 58
	s_cbranch_scc0 .LBB0_661
	v_readlane_b32 s6, v227, 10
	v_mov_b32_e32 v2, v178
	v_readlane_b32 s7, v227, 11
	s_andn2_b64 vcc, exec, s[6:7]
	v_readfirstlane_b32 s2, v2
	s_cbranch_vccnz .LBB0_568
	v_readlane_b32 s7, v226, 1
	s_mul_hi_i32 s6, s7, 0xb00000
	s_mul_i32 s7, s7, 0xb00000
	s_add_u32 s18, s70, s7
	s_addc_u32 s19, s71, s6
	s_ashr_i32 s6, s2, 6
	v_bfe_u32 v0, v2, 3, 3
	v_lshl_or_b32 v0, s6, 3, v0
	v_lshrrev_b32_e32 v3, 1, v0
	v_xor_b32_e32 v3, v3, v2
	v_lshlrev_b32_e32 v3, 4, v3
	v_lshlrev_b32_e32 v0, 11, v0
	s_movk_i32 s7, 0x70
	v_and_or_b32 v201, v3, s7, v0
	s_ashr_i32 s7, s2, 1
	s_and_b32 s20, s7, 0xffffff80
	s_and_b32 s21, s2, 0xc0
	v_readlane_b32 s8, v227, 13
	v_readlane_b32 s9, v227, 14
	s_add_u32 s64, s94, s8
	s_addc_u32 s2, s95, s9
	v_readlane_b32 s8, v227, 15
	v_readlane_b32 s9, v227, 16
	s_add_u32 s8, s18, s8
	s_addc_u32 s7, s19, s9
	s_lshl_b32 s22, s6, 10
	s_and_b32 s65, s2, 0xffff
	s_add_i32 s23, s22, 0x8000
	s_mov_b32 m0, s22
	s_and_b32 s9, s7, 0xffff
	s_mov_b32 s10, s66
	s_mov_b32 s11, s67
	s_and_b32 s2, s6, 1
	s_lshl_b32 s2, s2, 5
	s_bfe_u32 s7, s6, 0x10001
	s_lshl_b32 s7, s7, 4
	s_add_i32 s2, s2, s7
	s_lshr_b32 s7, s6, 2
	s_add_i32 s2, s2, s7
	v_bfe_u32 v248, v178, 3, 3
	v_lshl_add_u32 v248, v248, 1, s2
	v_lshlrev_b32_e32 v248, 11, v248
	v_and_b32_e32 v249, 0x70, v201
	v_or_b32_e32 v248, v248, v249
	buffer_load_dwordx4 v201, s[64:67], 0 offen lds
	s_mov_b32 m0, s23
	s_add_i32 s24, s22, 0x2000
	buffer_load_dwordx4 v248, s[8:11], 0 offen lds
	s_mov_b32 m0, s24
	s_add_i32 s25, s22, 0xa000
	buffer_load_dwordx4 v201, s[64:67], s67 offen lds
	s_mov_b32 m0, s25
	s_add_i32 s26, s22, 0x4000
	buffer_load_dwordx4 v248, s[8:11], s67 offen lds
	s_mov_b32 m0, s26
	s_add_i32 s27, s22, 0xc000
	buffer_load_dwordx4 v201, s[64:67], s83 offen lds
	s_mov_b32 m0, s27
	s_add_i32 s28, s22, 0x6000
	buffer_load_dwordx4 v248, s[8:11], s83 offen lds
	s_mov_b32 m0, s28
	s_add_i32 s29, s22, 0xe000
	buffer_load_dwordx4 v201, s[64:67], s90 offen lds
	s_mov_b32 m0, s29
	v_and_b32_e32 v202, 15, v2
	buffer_load_dwordx4 v248, s[8:11], s90 offen lds
	v_or_b32_e32 v0, s21, v202
	v_lshlrev_b32_e32 v0, 7, v0
	v_and_b32_e32 v3, 0x6400, v0
	v_bfe_u32 v4, v2, 4, 2
	v_lshrrev_b32_e32 v0, 1, v2
	v_bitop3_b32 v5, v4, v0, 7 bitop3:0x78
	v_lshlrev_b32_e32 v0, 7, v2
	v_and_b32_e32 v6, 0x380, v0
	v_or_b32_e32 v0, s20, v202
	v_and_b32_e32 v8, 1, v2
	v_readlane_b32 s8, v227, 53
	v_lshlrev_b32_e32 v7, 7, v0
	v_lshlrev_b32_e32 v0, 5, v8
	v_readlane_b32 s9, v227, 54
	v_lshl_or_b32 v5, v5, 4, v6
	s_mov_b32 s2, 0x8000
	v_lshl_add_u64 v[170:171], s[8:9], 0, v[0:1]
	v_lshlrev_b32_e32 v0, 5, v2
	v_ashrrev_i32_e32 v203, 1, v2
	v_or3_b32 v204, v3, v5, s2
	v_lshlrev_b32_e32 v4, 2, v4
	v_and_b32_e32 v0, 32, v0
	s_movk_i32 s2, 0xc400
	s_mov_b32 s30, 0
	v_cmp_eq_u32_e64 s[6:7], 0, v8
	v_or_b32_e32 v205, s20, v4
	v_lshl_add_u64 v[172:173], s[8:9], 0, v[0:1]
	v_lshl_add_u32 v206, v203, 2, v199
	v_and_or_b32 v207, v7, s2, v5
	v_lshlrev_b32_e32 v0, 2, v4
	s_mov_b32 s31, s72
	s_branch .LBB0_423

.LBB0_429:
	s_cmp_eq_u32 s15, 0x60800
	s_mov_b32 s2, 0x10000
	s_and_b32 s2, s13, 0x10000
	s_xor_b32 s10, s2, 0x10000
	s_add_i32 s35, s22, s10
	s_add_i32 s36, s15, 0xfffa0000
	s_add_i32 s37, s35, 0x8000
	s_mov_b32 s10, s66
	s_mov_b32 s11, s67
	s_waitcnt lgkmcnt(0)
	v_add_u32_e32 v228, s2, v207
	v_add_u32_e32 v229, s2, v204
	ds_read_b128 v[50:53], v229 offset:0
	ds_read_b128 v[54:57], v229 offset:0x800
	ds_read_b128 v[58:61], v229 offset:0x1000
	ds_read_b128 v[78:81], v229 offset:0x1800
	ds_read_b128 v[98:101], v228 offset:0
	ds_read_b128 v[118:121], v228 offset:0x800
	s_setprio 1
	s_mov_b32 m0, s35
	s_nop 0
	buffer_load_dwordx4 v201, s[64:67], s36 offen lds
	s_mov_b32 m0, s37
	s_nop 0
	buffer_load_dwordx4 v248, s[8:11], s36 offen lds
	s_add_i32 m0, s35, 0x2000
	s_add_i32 s36, s15, 0xfffc0000
	buffer_load_dwordx4 v201, s[64:67], s36 offen lds
	s_add_i32 m0, s35, 0xa000
	s_nop 0
	buffer_load_dwordx4 v248, s[8:11], s36 offen lds
	ds_read_b128 v[138:141], v228 offset:0x1000
	v_xor_b32_e32 v208, 64, v228
	s_branch .Lrot0_mid_l
.Lrot0_top_l:
	s_and_b32 s2, s13, 0x10000
	s_xor_b32 s10, s2, 0x10000
	s_add_i32 s35, s22, s10
	s_add_i32 s36, s15, 0xfffa0000
	s_add_i32 s37, s35, 0x8000
	s_mov_b32 s10, s66
	s_mov_b32 s11, s67
	v_add_u32_e32 v228, s2, v207
	v_add_u32_e32 v229, s2, v204
	ds_read_b128 v[50:53], v229 offset:0
	ds_read_b128 v[54:57], v229 offset:0x800
	ds_read_b128 v[58:61], v229 offset:0x1000
	ds_read_b128 v[78:81], v229 offset:0x1800
	ds_read_b128 v[98:101], v228 offset:0
	ds_read_b128 v[118:121], v228 offset:0x800
	s_setprio 1
	s_mov_b32 m0, s35
	s_nop 0
	buffer_load_dwordx4 v201, s[64:67], s36 offen lds
	s_mov_b32 m0, s37
	s_nop 0
	buffer_load_dwordx4 v248, s[8:11], s36 offen lds
	v_mfma_f32_16x16x32_bf16 v[42:45], v[232:235], v[138:141], v[42:45]
	v_mfma_f32_16x16x32_bf16 v[46:49], v[232:235], v[158:161], v[46:49]
	v_mfma_f32_16x16x32_bf16 v[34:37], v[232:235], v[162:165], v[34:37]
	v_mfma_f32_16x16x32_bf16 v[38:41], v[232:235], v[166:169], v[38:41]
	s_add_i32 m0, s35, 0x2000
	s_add_i32 s36, s15, 0xfffc0000
	buffer_load_dwordx4 v201, s[64:67], s36 offen lds
	v_mfma_f32_16x16x32_bf16 v[26:29], v[236:239], v[138:141], v[26:29]
	v_mfma_f32_16x16x32_bf16 v[30:33], v[236:239], v[158:161], v[30:33]
	v_mfma_f32_16x16x32_bf16 v[18:21], v[236:239], v[162:165], v[18:21]
	v_mfma_f32_16x16x32_bf16 v[22:25], v[236:239], v[166:169], v[22:25]
	s_add_i32 m0, s35, 0xa000
	s_nop 0
	buffer_load_dwordx4 v248, s[8:11], s36 offen lds
	v_mfma_f32_16x16x32_bf16 v[10:13], v[240:243], v[138:141], v[10:13]
	v_mfma_f32_16x16x32_bf16 v[14:17], v[240:243], v[158:161], v[14:17]
	v_mfma_f32_16x16x32_bf16 v[2:5], v[240:243], v[162:165], v[2:5]
	v_mfma_f32_16x16x32_bf16 v[6:9], v[240:243], v[166:169], v[6:9]
	ds_read_b128 v[138:141], v228 offset:0x1000
	v_xor_b32_e32 v208, 64, v228
.Lrot0_mid_l:
	s_waitcnt lgkmcnt(2)
	s_nop 0
	v_mfma_f32_16x16x32_bf16 v[150:153], v[98:101], v[50:53], v[150:153]
	v_mfma_f32_16x16x32_bf16 v[154:157], v[98:101], v[54:57], v[154:157]
	v_mfma_f32_16x16x32_bf16 v[142:145], v[98:101], v[58:61], v[142:145]
	v_mfma_f32_16x16x32_bf16 v[98:101], v[98:101], v[78:81], v[146:149]
	s_add_i32 m0, s35, 0x4000
	s_add_i32 s36, s15, 0xfffe0000
	buffer_load_dwordx4 v201, s[64:67], s36 offen lds
	ds_read_b128 v[146:149], v228 offset:0x1800
	s_waitcnt lgkmcnt(2)
	s_nop 0
	v_mfma_f32_16x16x32_bf16 v[130:133], v[118:121], v[50:53], v[130:133]
	v_mfma_f32_16x16x32_bf16 v[134:137], v[118:121], v[54:57], v[134:137]
	v_mfma_f32_16x16x32_bf16 v[122:125], v[118:121], v[58:61], v[122:125]
	v_mfma_f32_16x16x32_bf16 v[118:121], v[118:121], v[78:81], v[126:129]
	s_add_i32 m0, s35, 0xc000
	s_nop 0
	buffer_load_dwordx4 v248, s[8:11], s36 offen lds
	ds_read_b128 v[126:129], v228 offset:0x2000
	s_waitcnt lgkmcnt(2)
	s_nop 0
	v_mfma_f32_16x16x32_bf16 v[110:113], v[138:141], v[50:53], v[110:113]
	v_mfma_f32_16x16x32_bf16 v[114:117], v[138:141], v[54:57], v[114:117]
	v_mfma_f32_16x16x32_bf16 v[102:105], v[138:141], v[58:61], v[102:105]
	v_mfma_f32_16x16x32_bf16 v[106:109], v[138:141], v[78:81], v[106:109]
	s_add_i32 m0, s35, 0x6000
	s_nop 0
	buffer_load_dwordx4 v201, s[64:67], s15 offen lds
	ds_read_b128 v[138:141], v228 offset:0x2800
	s_waitcnt lgkmcnt(2)
	s_nop 0
	v_mfma_f32_16x16x32_bf16 v[90:93], v[146:149], v[50:53], v[90:93]
	v_mfma_f32_16x16x32_bf16 v[94:97], v[146:149], v[54:57], v[94:97]
	v_mfma_f32_16x16x32_bf16 v[82:85], v[146:149], v[58:61], v[82:85]
	v_mfma_f32_16x16x32_bf16 v[86:89], v[146:149], v[78:81], v[86:89]
	s_add_i32 m0, s35, 0xe000
	s_nop 0
	buffer_load_dwordx4 v248, s[8:11], s15 offen lds
	ds_read_b128 v[146:149], v228 offset:0x3000
	s_waitcnt lgkmcnt(2)
	s_nop 0
	v_mfma_f32_16x16x32_bf16 v[70:73], v[126:129], v[50:53], v[70:73]
	v_mfma_f32_16x16x32_bf16 v[74:77], v[126:129], v[54:57], v[74:77]
	v_mfma_f32_16x16x32_bf16 v[62:65], v[126:129], v[58:61], v[62:65]
	v_mfma_f32_16x16x32_bf16 v[66:69], v[126:129], v[78:81], v[66:69]
	ds_read_b128 v[126:129], v228 offset:0x3800
	s_waitcnt lgkmcnt(2)
	v_xor_b32_e32 v166, 64, v229
	v_mfma_f32_16x16x32_bf16 v[42:45], v[138:141], v[50:53], v[42:45]
	v_mfma_f32_16x16x32_bf16 v[46:49], v[138:141], v[54:57], v[46:49]
	v_mfma_f32_16x16x32_bf16 v[34:37], v[138:141], v[58:61], v[34:37]
	v_mfma_f32_16x16x32_bf16 v[38:41], v[138:141], v[78:81], v[38:41]
	ds_read_b128 v[138:141], v166 offset:0
	ds_read_b128 v[158:161], v166 offset:0x800
	ds_read_b128 v[162:165], v166 offset:0x1000
	s_waitcnt lgkmcnt(4)
	s_nop 0
	v_mfma_f32_16x16x32_bf16 v[26:29], v[146:149], v[50:53], v[26:29]
	v_mfma_f32_16x16x32_bf16 v[30:33], v[146:149], v[54:57], v[30:33]
	v_mfma_f32_16x16x32_bf16 v[18:21], v[146:149], v[58:61], v[18:21]
	v_mfma_f32_16x16x32_bf16 v[22:25], v[146:149], v[78:81], v[22:25]
	ds_read_b128 v[166:169], v166 offset:0x1800
	ds_read_b128 v[146:149], v208 offset:0
	ds_read_b128 v[174:177], v208 offset:0x800
	s_waitcnt lgkmcnt(6)
	s_nop 0
	v_mfma_f32_16x16x32_bf16 v[10:13], v[126:129], v[50:53], v[10:13]
	v_mfma_f32_16x16x32_bf16 v[14:17], v[126:129], v[54:57], v[14:17]
	v_mfma_f32_16x16x32_bf16 v[2:5], v[126:129], v[58:61], v[2:5]
	v_mfma_f32_16x16x32_bf16 v[6:9], v[126:129], v[78:81], v[6:9]
	ds_read_b128 v[50:53], v208 offset:0x1000
	s_waitcnt lgkmcnt(2)
	s_nop 0
	v_mfma_f32_16x16x32_bf16 v[150:153], v[146:149], v[138:141], v[150:153]
	v_mfma_f32_16x16x32_bf16 v[154:157], v[146:149], v[158:161], v[154:157]
	v_mfma_f32_16x16x32_bf16 v[142:145], v[146:149], v[162:165], v[142:145]
	v_mfma_f32_16x16x32_bf16 v[146:149], v[146:149], v[166:169], v[98:101]
	ds_read_b128 v[54:57], v208 offset:0x1800
	s_waitcnt lgkmcnt(2)
	s_nop 0
	v_mfma_f32_16x16x32_bf16 v[130:133], v[174:177], v[138:141], v[130:133]
	v_mfma_f32_16x16x32_bf16 v[134:137], v[174:177], v[158:161], v[134:137]
	v_mfma_f32_16x16x32_bf16 v[122:125], v[174:177], v[162:165], v[122:125]
	v_mfma_f32_16x16x32_bf16 v[126:129], v[174:177], v[166:169], v[118:121]
	ds_read_b128 v[58:61], v208 offset:0x2000
	ds_read_b128 v[232:235], v208 offset:0x2800
	s_waitcnt lgkmcnt(3)
	s_nop 0
	v_mfma_f32_16x16x32_bf16 v[110:113], v[50:53], v[138:141], v[110:113]
	v_mfma_f32_16x16x32_bf16 v[114:117], v[50:53], v[158:161], v[114:117]
	v_mfma_f32_16x16x32_bf16 v[102:105], v[50:53], v[162:165], v[102:105]
	v_mfma_f32_16x16x32_bf16 v[106:109], v[50:53], v[166:169], v[106:109]
	ds_read_b128 v[236:239], v208 offset:0x3000
	s_waitcnt lgkmcnt(3)
	s_nop 0
	v_mfma_f32_16x16x32_bf16 v[90:93], v[54:57], v[138:141], v[90:93]
	v_mfma_f32_16x16x32_bf16 v[94:97], v[54:57], v[158:161], v[94:97]
	v_mfma_f32_16x16x32_bf16 v[82:85], v[54:57], v[162:165], v[82:85]
	v_mfma_f32_16x16x32_bf16 v[86:89], v[54:57], v[166:169], v[86:89]
	ds_read_b128 v[240:243], v208 offset:0x3800
	s_waitcnt lgkmcnt(3)
	s_nop 0
	v_mfma_f32_16x16x32_bf16 v[70:73], v[58:61], v[138:141], v[70:73]
	v_mfma_f32_16x16x32_bf16 v[74:77], v[58:61], v[158:161], v[74:77]
	v_mfma_f32_16x16x32_bf16 v[62:65], v[58:61], v[162:165], v[62:65]
	v_mfma_f32_16x16x32_bf16 v[66:69], v[58:61], v[166:169], v[66:69]
	s_setprio 0
	s_waitcnt lgkmcnt(0)
	s_waitcnt vmcnt(0)
	s_add_i32 s13, s13, 0x10000
	s_addk_i32 s15, 0x80
	s_cmp_eq_u32 s15, 0x60800
	s_mov_b32 s2, 0x10000
	s_barrier
	s_cbranch_scc0 .Lrot0_top_l

.LBB0_431:
	s_lshl_b32 s2, s20, 2
	s_add_i32 s68, s34, s2
	v_lshl_add_u64 v[50:51], s[68:69], 0, v[0:1]
	s_waitcnt vmcnt(0)
	s_waitcnt vmcnt(0)
	ds_read_b128 v[166:169], v50
	ds_read_b128 v[162:165], v50 offset:64
	ds_read_b128 v[158:161], v50 offset:128
	ds_read_b128 v[138:141], v50 offset:192
	ds_read_b128 v[118:121], v50 offset:256
	ds_read_b128 v[98:101], v50 offset:320
	ds_read_b128 v[78:81], v50 offset:384
	ds_read_b128 v[58:61], v50 offset:448
	s_load_dword s2, s[78:79], 0x0
	v_mov_b32_e32 v50, 0
	v_mov_b32_e32 v51, 0
	v_mov_b32_e32 v52, 0
	v_mov_b32_e32 v53, 0
	s_waitcnt lgkmcnt(0)
	s_add_i32 s31, s2, s31
	s_cmpk_lt_i32 s31, 0x580
	s_cselect_b64 s[10:11], -1, 0
	s_and_b64 vcc, exec, s[10:11]
	v_mov_b32_e32 v54, 0
	v_mov_b32_e32 v55, 0
	v_mov_b32_e32 v56, 0
	v_mov_b32_e32 v57, 0
	s_cbranch_vccz .LBB0_433
	s_ashr_i32 s2, s31, 31
	s_lshr_b32 s2, s2, 29
	s_add_i32 s2, s31, s2
	s_ashr_i32 s8, s2, 3
	s_and_b32 s2, s2, -8
	s_sub_i32 s2, s31, s2
	s_cmp_lt_i32 s2, 0
	s_cselect_b32 s9, s73, 0xb0
	s_mul_i32 s2, s9, s2
	s_add_i32 s2, s2, s8
	s_mul_hi_i32 s8, s2, 0x2e8ba2e9
	s_lshr_b32 s9, s8, 31
	s_ashr_i32 s8, s8, 4
	s_add_i32 s8, s8, s9
	s_mul_i32 s9, s8, 0x58
	s_sub_i32 s2, s2, s9
	s_bfe_i32 s9, s2, 0x80000
	s_bfe_u32 s9, s9, 0x2000d
	s_add_i32 s9, s2, s9
	s_bfe_i32 s13, s9, 0x80000
	s_and_b32 s9, s9, 0xfc
	s_sub_i32 s2, s2, s9
	s_sext_i32_i8 s2, s2
	s_lshl_b32 s8, s8, 10
	s_lshl_b32 s2, s2, 8
	s_sext_i32_i16 s13, s13
	s_add_i32 s8, s2, s8
	s_lshl_b32 s2, s13, 6
	s_ashr_i32 s9, s8, 31
	s_and_b32 s34, s2, 0xffffff00
	v_add_u32_e32 v50, s8, v203
	s_lshl_b64 s[8:9], s[8:9], 11
	s_add_u32 s64, s94, s8
	s_addc_u32 s2, s95, s9
	s_ashr_i32 s35, s34, 31
	v_ashrrev_i32_e32 v51, 31, v50
	s_lshl_b64 s[8:9], s[34:35], 11
	v_lshlrev_b64 v[50:51], 6, v[50:51]
	s_add_u32 s36, s18, s8
	s_mov_b32 m0, s22
	v_lshl_add_u64 v[54:55], v[172:173], 0, v[50:51]
	s_addc_u32 s8, s19, s9
	s_and_b32 s65, s2, 0xffff
	global_load_dwordx4 v[50:53], v[54:55], off
	s_nop 0
	global_load_dwordx4 v[54:57], v[54:55], off offset:16
	s_and_b32 s37, s8, 0xffff
	s_mov_b32 s38, s66
	s_mov_b32 s39, s67
	buffer_load_dwordx4 v201, s[64:67], 0 offen lds
	s_mov_b32 m0, s23
	s_nop 0
	buffer_load_dwordx4 v248, s[36:39], 0 offen lds
	s_mov_b32 m0, s24
	s_nop 0
	buffer_load_dwordx4 v201, s[64:67], s67 offen lds
	s_mov_b32 m0, s25
	s_nop 0
	buffer_load_dwordx4 v248, s[36:39], s67 offen lds
	s_mov_b32 m0, s26
	s_nop 0
	buffer_load_dwordx4 v201, s[64:67], s83 offen lds
	s_mov_b32 m0, s27
	s_nop 0
	buffer_load_dwordx4 v248, s[36:39], s83 offen lds
	s_mov_b32 m0, s28
	s_nop 0
	buffer_load_dwordx4 v201, s[64:67], s90 offen lds
	s_mov_b32 m0, s29
	s_nop 0
	buffer_load_dwordx4 v248, s[36:39], s90 offen lds
.LBB0_433:
	v_add_u32_e32 v177, s12, v205
	s_or_b32 s2, s14, s21
	s_ashr_i32 s2, s2, 1
	v_or_b32_e32 v176, s2, v202
	v_mov_b64_e32 v[174:175], s[76:77]
	s_movk_i32 s8, 0x1580
	v_mad_i64_i32 v[174:175], s[8:9], v177, s8, v[174:175]
	v_ashrrev_i32_e32 v177, 31, v176
	v_lshl_add_u64 v[174:175], v[176:177], 1, v[174:175]
	s_cmpk_lt_i32 s2, 0xaa1
	s_cbranch_scc0 .Lsw_epi_done
	v_lshlrev_b32_e32 v236, 1, v202
	v_mov_b32_e32 v237, 0
	v_lshl_add_u64 v[174:175], v[174:175], 0, v[236:237]
	v_mul_f32_e32 v228, v150, v166
	v_mul_f32_e32 v229, v142, v166
	v_mul_f32_e32 v230, 0xbfb8aa3b, v228
	v_mul_f32_e32 v231, 0xbfb8aa3b, v229
	v_exp_f32_e32 v230, v230
	v_exp_f32_e32 v231, v231
	v_mul_f32_e32 v232, v154, v166
	v_mul_f32_e32 v233, v146, v166
	v_add_f32_e32 v230, 1.0, v230
	v_add_f32_e32 v231, 1.0, v231
	v_rcp_f32_e32 v230, v230
	v_rcp_f32_e32 v231, v231
	v_mul_f32_e32 v228, v228, v230
	v_mul_f32_e32 v229, v229, v231
	v_mul_f32_e32 v232, v232, v228
	v_mul_f32_e32 v233, v233, v229
	v_cvt_pk_bf16_f32 v234, v232, v233
	global_store_dword v[174:175], v234, off
	v_lshl_add_u64 v[174:175], v[174:175], 0, s[98:99]
	v_mul_f32_e32 v228, v151, v167
	v_mul_f32_e32 v229, v143, v167
	v_mul_f32_e32 v230, 0xbfb8aa3b, v228
	v_mul_f32_e32 v231, 0xbfb8aa3b, v229
	v_exp_f32_e32 v230, v230
	v_exp_f32_e32 v231, v231
	v_mul_f32_e32 v232, v155, v167
	v_mul_f32_e32 v233, v147, v167
	v_add_f32_e32 v230, 1.0, v230
	v_add_f32_e32 v231, 1.0, v231
	v_rcp_f32_e32 v230, v230
	v_rcp_f32_e32 v231, v231
	v_mul_f32_e32 v228, v228, v230
	v_mul_f32_e32 v229, v229, v231
	v_mul_f32_e32 v232, v232, v228
	v_mul_f32_e32 v233, v233, v229
	v_cvt_pk_bf16_f32 v235, v232, v233
	global_store_dword v[174:175], v235, off
	v_lshl_add_u64 v[174:175], v[174:175], 0, s[98:99]
	v_mul_f32_e32 v228, v152, v168
	v_mul_f32_e32 v229, v144, v168
	v_mul_f32_e32 v230, 0xbfb8aa3b, v228
	v_mul_f32_e32 v231, 0xbfb8aa3b, v229
	v_exp_f32_e32 v230, v230
	v_exp_f32_e32 v231, v231
	v_mul_f32_e32 v232, v156, v168
	v_mul_f32_e32 v233, v148, v168
	v_add_f32_e32 v230, 1.0, v230
	v_add_f32_e32 v231, 1.0, v231
	v_rcp_f32_e32 v230, v230
	v_rcp_f32_e32 v231, v231
	v_mul_f32_e32 v228, v228, v230
	v_mul_f32_e32 v229, v229, v231
	v_mul_f32_e32 v232, v232, v228
	v_mul_f32_e32 v233, v233, v229
	v_cvt_pk_bf16_f32 v234, v232, v233
	global_store_dword v[174:175], v234, off
	v_lshl_add_u64 v[174:175], v[174:175], 0, s[98:99]
	v_mul_f32_e32 v228, v153, v169
	v_mul_f32_e32 v229, v145, v169
	v_mul_f32_e32 v230, 0xbfb8aa3b, v228
	v_mul_f32_e32 v231, 0xbfb8aa3b, v229
	v_exp_f32_e32 v230, v230
	v_exp_f32_e32 v231, v231
	v_mul_f32_e32 v232, v157, v169
	v_mul_f32_e32 v233, v149, v169
	v_add_f32_e32 v230, 1.0, v230
	v_add_f32_e32 v231, 1.0, v231
	v_rcp_f32_e32 v230, v230
	v_rcp_f32_e32 v231, v231
	v_mul_f32_e32 v228, v228, v230
	v_mul_f32_e32 v229, v229, v231
	v_mul_f32_e32 v232, v232, v228
	v_mul_f32_e32 v233, v233, v229
	v_cvt_pk_bf16_f32 v235, v232, v233
	global_store_dword v[174:175], v235, off
	v_lshl_add_u64 v[174:175], v[174:175], 0, s[98:99]
	v_lshl_add_u64 v[174:175], v[174:175], 0, s[44:45]
	v_mul_f32_e32 v228, v130, v162
	v_mul_f32_e32 v229, v122, v162
	v_mul_f32_e32 v230, 0xbfb8aa3b, v228
	v_mul_f32_e32 v231, 0xbfb8aa3b, v229
	v_exp_f32_e32 v230, v230
	v_exp_f32_e32 v231, v231
	v_mul_f32_e32 v232, v134, v162
	v_mul_f32_e32 v233, v126, v162
	v_add_f32_e32 v230, 1.0, v230
	v_add_f32_e32 v231, 1.0, v231
	v_rcp_f32_e32 v230, v230
	v_rcp_f32_e32 v231, v231
	v_mul_f32_e32 v228, v228, v230
	v_mul_f32_e32 v229, v229, v231
	v_mul_f32_e32 v232, v232, v228
	v_mul_f32_e32 v233, v233, v229
	v_cvt_pk_bf16_f32 v234, v232, v233
	global_store_dword v[174:175], v234, off
	v_lshl_add_u64 v[174:175], v[174:175], 0, s[98:99]
	v_mul_f32_e32 v228, v131, v163
	v_mul_f32_e32 v229, v123, v163
	v_mul_f32_e32 v230, 0xbfb8aa3b, v228
	v_mul_f32_e32 v231, 0xbfb8aa3b, v229
	v_exp_f32_e32 v230, v230
	v_exp_f32_e32 v231, v231
	v_mul_f32_e32 v232, v135, v163
	v_mul_f32_e32 v233, v127, v163
	v_add_f32_e32 v230, 1.0, v230
	v_add_f32_e32 v231, 1.0, v231
	v_rcp_f32_e32 v230, v230
	v_rcp_f32_e32 v231, v231
	v_mul_f32_e32 v228, v228, v230
	v_mul_f32_e32 v229, v229, v231
	v_mul_f32_e32 v232, v232, v228
	v_mul_f32_e32 v233, v233, v229
	v_cvt_pk_bf16_f32 v235, v232, v233
	global_store_dword v[174:175], v235, off
	v_lshl_add_u64 v[174:175], v[174:175], 0, s[98:99]
	v_mul_f32_e32 v228, v132, v164
	v_mul_f32_e32 v229, v124, v164
	v_mul_f32_e32 v230, 0xbfb8aa3b, v228
	v_mul_f32_e32 v231, 0xbfb8aa3b, v229
	v_exp_f32_e32 v230, v230
	v_exp_f32_e32 v231, v231
	v_mul_f32_e32 v232, v136, v164
	v_mul_f32_e32 v233, v128, v164
	v_add_f32_e32 v230, 1.0, v230
	v_add_f32_e32 v231, 1.0, v231
	v_rcp_f32_e32 v230, v230
	v_rcp_f32_e32 v231, v231
	v_mul_f32_e32 v228, v228, v230
	v_mul_f32_e32 v229, v229, v231
	v_mul_f32_e32 v232, v232, v228
	v_mul_f32_e32 v233, v233, v229
	v_cvt_pk_bf16_f32 v234, v232, v233
	global_store_dword v[174:175], v234, off
	v_lshl_add_u64 v[174:175], v[174:175], 0, s[98:99]
	v_mul_f32_e32 v228, v133, v165
	v_mul_f32_e32 v229, v125, v165
	v_mul_f32_e32 v230, 0xbfb8aa3b, v228
	v_mul_f32_e32 v231, 0xbfb8aa3b, v229
	v_exp_f32_e32 v230, v230
	v_exp_f32_e32 v231, v231
	v_mul_f32_e32 v232, v137, v165
	v_mul_f32_e32 v233, v129, v165
	v_add_f32_e32 v230, 1.0, v230
	v_add_f32_e32 v231, 1.0, v231
	v_rcp_f32_e32 v230, v230
	v_rcp_f32_e32 v231, v231
	v_mul_f32_e32 v228, v228, v230
	v_mul_f32_e32 v229, v229, v231
	v_mul_f32_e32 v232, v232, v228
	v_mul_f32_e32 v233, v233, v229
	v_cvt_pk_bf16_f32 v235, v232, v233
	global_store_dword v[174:175], v235, off
	v_lshl_add_u64 v[174:175], v[174:175], 0, s[98:99]
	v_lshl_add_u64 v[174:175], v[174:175], 0, s[44:45]
	v_mul_f32_e32 v228, v110, v158
	v_mul_f32_e32 v229, v102, v158
	v_mul_f32_e32 v230, 0xbfb8aa3b, v228
	v_mul_f32_e32 v231, 0xbfb8aa3b, v229
	v_exp_f32_e32 v230, v230
	v_exp_f32_e32 v231, v231
	v_mul_f32_e32 v232, v114, v158
	v_mul_f32_e32 v233, v106, v158
	v_add_f32_e32 v230, 1.0, v230
	v_add_f32_e32 v231, 1.0, v231
	v_rcp_f32_e32 v230, v230
	v_rcp_f32_e32 v231, v231
	v_mul_f32_e32 v228, v228, v230
	v_mul_f32_e32 v229, v229, v231
	v_mul_f32_e32 v232, v232, v228
	v_mul_f32_e32 v233, v233, v229
	v_cvt_pk_bf16_f32 v234, v232, v233
	global_store_dword v[174:175], v234, off
	v_lshl_add_u64 v[174:175], v[174:175], 0, s[98:99]
	v_mul_f32_e32 v228, v111, v159
	v_mul_f32_e32 v229, v103, v159
	v_mul_f32_e32 v230, 0xbfb8aa3b, v228
	v_mul_f32_e32 v231, 0xbfb8aa3b, v229
	v_exp_f32_e32 v230, v230
	v_exp_f32_e32 v231, v231
	v_mul_f32_e32 v232, v115, v159
	v_mul_f32_e32 v233, v107, v159
	v_add_f32_e32 v230, 1.0, v230
	v_add_f32_e32 v231, 1.0, v231
	v_rcp_f32_e32 v230, v230
	v_rcp_f32_e32 v231, v231
	v_mul_f32_e32 v228, v228, v230
	v_mul_f32_e32 v229, v229, v231
	v_mul_f32_e32 v232, v232, v228
	v_mul_f32_e32 v233, v233, v229
	v_cvt_pk_bf16_f32 v235, v232, v233
	global_store_dword v[174:175], v235, off
	v_lshl_add_u64 v[174:175], v[174:175], 0, s[98:99]
	v_mul_f32_e32 v228, v112, v160
	v_mul_f32_e32 v229, v104, v160
	v_mul_f32_e32 v230, 0xbfb8aa3b, v228
	v_mul_f32_e32 v231, 0xbfb8aa3b, v229
	v_exp_f32_e32 v230, v230
	v_exp_f32_e32 v231, v231
	v_mul_f32_e32 v232, v116, v160
	v_mul_f32_e32 v233, v108, v160
	v_add_f32_e32 v230, 1.0, v230
	v_add_f32_e32 v231, 1.0, v231
	v_rcp_f32_e32 v230, v230
	v_rcp_f32_e32 v231, v231
	v_mul_f32_e32 v228, v228, v230
	v_mul_f32_e32 v229, v229, v231
	v_mul_f32_e32 v232, v232, v228
	v_mul_f32_e32 v233, v233, v229
	v_cvt_pk_bf16_f32 v234, v232, v233
	global_store_dword v[174:175], v234, off
	v_lshl_add_u64 v[174:175], v[174:175], 0, s[98:99]
	v_mul_f32_e32 v228, v113, v161
	v_mul_f32_e32 v229, v105, v161
	v_mul_f32_e32 v230, 0xbfb8aa3b, v228
	v_mul_f32_e32 v231, 0xbfb8aa3b, v229
	v_exp_f32_e32 v230, v230
	v_exp_f32_e32 v231, v231
	v_mul_f32_e32 v232, v117, v161
	v_mul_f32_e32 v233, v109, v161
	v_add_f32_e32 v230, 1.0, v230
	v_add_f32_e32 v231, 1.0, v231
	v_rcp_f32_e32 v230, v230
	v_rcp_f32_e32 v231, v231
	v_mul_f32_e32 v228, v228, v230
	v_mul_f32_e32 v229, v229, v231
	v_mul_f32_e32 v232, v232, v228
	v_mul_f32_e32 v233, v233, v229
	v_cvt_pk_bf16_f32 v235, v232, v233
	global_store_dword v[174:175], v235, off
	v_lshl_add_u64 v[174:175], v[174:175], 0, s[98:99]
	v_lshl_add_u64 v[174:175], v[174:175], 0, s[44:45]
	v_mul_f32_e32 v228, v90, v138
	v_mul_f32_e32 v229, v82, v138
	v_mul_f32_e32 v230, 0xbfb8aa3b, v228
	v_mul_f32_e32 v231, 0xbfb8aa3b, v229
	v_exp_f32_e32 v230, v230
	v_exp_f32_e32 v231, v231
	v_mul_f32_e32 v232, v94, v138
	v_mul_f32_e32 v233, v86, v138
	v_add_f32_e32 v230, 1.0, v230
	v_add_f32_e32 v231, 1.0, v231
	v_rcp_f32_e32 v230, v230
	v_rcp_f32_e32 v231, v231
	v_mul_f32_e32 v228, v228, v230
	v_mul_f32_e32 v229, v229, v231
	v_mul_f32_e32 v232, v232, v228
	v_mul_f32_e32 v233, v233, v229
	v_cvt_pk_bf16_f32 v234, v232, v233
	global_store_dword v[174:175], v234, off
	v_lshl_add_u64 v[174:175], v[174:175], 0, s[98:99]
	v_mul_f32_e32 v228, v91, v139
	v_mul_f32_e32 v229, v83, v139
	v_mul_f32_e32 v230, 0xbfb8aa3b, v228
	v_mul_f32_e32 v231, 0xbfb8aa3b, v229
	v_exp_f32_e32 v230, v230
	v_exp_f32_e32 v231, v231
	v_mul_f32_e32 v232, v95, v139
	v_mul_f32_e32 v233, v87, v139
	v_add_f32_e32 v230, 1.0, v230
	v_add_f32_e32 v231, 1.0, v231
	v_rcp_f32_e32 v230, v230
	v_rcp_f32_e32 v231, v231
	v_mul_f32_e32 v228, v228, v230
	v_mul_f32_e32 v229, v229, v231
	v_mul_f32_e32 v232, v232, v228
	v_mul_f32_e32 v233, v233, v229
	v_cvt_pk_bf16_f32 v235, v232, v233
	global_store_dword v[174:175], v235, off
	v_lshl_add_u64 v[174:175], v[174:175], 0, s[98:99]
	v_mul_f32_e32 v228, v92, v140
	v_mul_f32_e32 v229, v84, v140
	v_mul_f32_e32 v230, 0xbfb8aa3b, v228
	v_mul_f32_e32 v231, 0xbfb8aa3b, v229
	v_exp_f32_e32 v230, v230
	v_exp_f32_e32 v231, v231
	v_mul_f32_e32 v232, v96, v140
	v_mul_f32_e32 v233, v88, v140
	v_add_f32_e32 v230, 1.0, v230
	v_add_f32_e32 v231, 1.0, v231
	v_rcp_f32_e32 v230, v230
	v_rcp_f32_e32 v231, v231
	v_mul_f32_e32 v228, v228, v230
	v_mul_f32_e32 v229, v229, v231
	v_mul_f32_e32 v232, v232, v228
	v_mul_f32_e32 v233, v233, v229
	v_cvt_pk_bf16_f32 v234, v232, v233
	global_store_dword v[174:175], v234, off
	v_lshl_add_u64 v[174:175], v[174:175], 0, s[98:99]
	v_mul_f32_e32 v228, v93, v141
	v_mul_f32_e32 v229, v85, v141
	v_mul_f32_e32 v230, 0xbfb8aa3b, v228
	v_mul_f32_e32 v231, 0xbfb8aa3b, v229
	v_exp_f32_e32 v230, v230
	v_exp_f32_e32 v231, v231
	v_mul_f32_e32 v232, v97, v141
	v_mul_f32_e32 v233, v89, v141
	v_add_f32_e32 v230, 1.0, v230
	v_add_f32_e32 v231, 1.0, v231
	v_rcp_f32_e32 v230, v230
	v_rcp_f32_e32 v231, v231
	v_mul_f32_e32 v228, v228, v230
	v_mul_f32_e32 v229, v229, v231
	v_mul_f32_e32 v232, v232, v228
	v_mul_f32_e32 v233, v233, v229
	v_cvt_pk_bf16_f32 v235, v232, v233
	global_store_dword v[174:175], v235, off
	v_lshl_add_u64 v[174:175], v[174:175], 0, s[98:99]
	v_lshl_add_u64 v[174:175], v[174:175], 0, s[44:45]
	v_mul_f32_e32 v228, v70, v118
	v_mul_f32_e32 v229, v62, v118
	v_mul_f32_e32 v230, 0xbfb8aa3b, v228
	v_mul_f32_e32 v231, 0xbfb8aa3b, v229
	v_exp_f32_e32 v230, v230
	v_exp_f32_e32 v231, v231
	v_mul_f32_e32 v232, v74, v118
	v_mul_f32_e32 v233, v66, v118
	v_add_f32_e32 v230, 1.0, v230
	v_add_f32_e32 v231, 1.0, v231
	v_rcp_f32_e32 v230, v230
	v_rcp_f32_e32 v231, v231
	v_mul_f32_e32 v228, v228, v230
	v_mul_f32_e32 v229, v229, v231
	v_mul_f32_e32 v232, v232, v228
	v_mul_f32_e32 v233, v233, v229
	v_cvt_pk_bf16_f32 v234, v232, v233
	global_store_dword v[174:175], v234, off
	v_lshl_add_u64 v[174:175], v[174:175], 0, s[98:99]
	v_mul_f32_e32 v228, v71, v119
	v_mul_f32_e32 v229, v63, v119
	v_mul_f32_e32 v230, 0xbfb8aa3b, v228
	v_mul_f32_e32 v231, 0xbfb8aa3b, v229
	v_exp_f32_e32 v230, v230
	v_exp_f32_e32 v231, v231
	v_mul_f32_e32 v232, v75, v119
	v_mul_f32_e32 v233, v67, v119
	v_add_f32_e32 v230, 1.0, v230
	v_add_f32_e32 v231, 1.0, v231
	v_rcp_f32_e32 v230, v230
	v_rcp_f32_e32 v231, v231
	v_mul_f32_e32 v228, v228, v230
	v_mul_f32_e32 v229, v229, v231
	v_mul_f32_e32 v232, v232, v228
	v_mul_f32_e32 v233, v233, v229
	v_cvt_pk_bf16_f32 v235, v232, v233
	global_store_dword v[174:175], v235, off
	v_lshl_add_u64 v[174:175], v[174:175], 0, s[98:99]
	v_mul_f32_e32 v228, v72, v120
	v_mul_f32_e32 v229, v64, v120
	v_mul_f32_e32 v230, 0xbfb8aa3b, v228
	v_mul_f32_e32 v231, 0xbfb8aa3b, v229
	v_exp_f32_e32 v230, v230
	v_exp_f32_e32 v231, v231
	v_mul_f32_e32 v232, v76, v120
	v_mul_f32_e32 v233, v68, v120
	v_add_f32_e32 v230, 1.0, v230
	v_add_f32_e32 v231, 1.0, v231
	v_rcp_f32_e32 v230, v230
	v_rcp_f32_e32 v231, v231
	v_mul_f32_e32 v228, v228, v230
	v_mul_f32_e32 v229, v229, v231
	v_mul_f32_e32 v232, v232, v228
	v_mul_f32_e32 v233, v233, v229
	v_cvt_pk_bf16_f32 v234, v232, v233
	global_store_dword v[174:175], v234, off
	v_lshl_add_u64 v[174:175], v[174:175], 0, s[98:99]
	v_mul_f32_e32 v228, v73, v121
	v_mul_f32_e32 v229, v65, v121
	v_mul_f32_e32 v230, 0xbfb8aa3b, v228
	v_mul_f32_e32 v231, 0xbfb8aa3b, v229
	v_exp_f32_e32 v230, v230
	v_exp_f32_e32 v231, v231
	v_mul_f32_e32 v232, v77, v121
	v_mul_f32_e32 v233, v69, v121
	v_add_f32_e32 v230, 1.0, v230
	v_add_f32_e32 v231, 1.0, v231
	v_rcp_f32_e32 v230, v230
	v_rcp_f32_e32 v231, v231
	v_mul_f32_e32 v228, v228, v230
	v_mul_f32_e32 v229, v229, v231
	v_mul_f32_e32 v232, v232, v228
	v_mul_f32_e32 v233, v233, v229
	v_cvt_pk_bf16_f32 v235, v232, v233
	global_store_dword v[174:175], v235, off
	v_lshl_add_u64 v[174:175], v[174:175], 0, s[98:99]
	v_lshl_add_u64 v[174:175], v[174:175], 0, s[44:45]
	v_mul_f32_e32 v228, v42, v98
	v_mul_f32_e32 v229, v34, v98
	v_mul_f32_e32 v230, 0xbfb8aa3b, v228
	v_mul_f32_e32 v231, 0xbfb8aa3b, v229
	v_exp_f32_e32 v230, v230
	v_exp_f32_e32 v231, v231
	v_mul_f32_e32 v232, v46, v98
	v_mul_f32_e32 v233, v38, v98
	v_add_f32_e32 v230, 1.0, v230
	v_add_f32_e32 v231, 1.0, v231
	v_rcp_f32_e32 v230, v230
	v_rcp_f32_e32 v231, v231
	v_mul_f32_e32 v228, v228, v230
	v_mul_f32_e32 v229, v229, v231
	v_mul_f32_e32 v232, v232, v228
	v_mul_f32_e32 v233, v233, v229
	v_cvt_pk_bf16_f32 v234, v232, v233
	global_store_dword v[174:175], v234, off
	v_lshl_add_u64 v[174:175], v[174:175], 0, s[98:99]
	v_mul_f32_e32 v228, v43, v99
	v_mul_f32_e32 v229, v35, v99
	v_mul_f32_e32 v230, 0xbfb8aa3b, v228
	v_mul_f32_e32 v231, 0xbfb8aa3b, v229
	v_exp_f32_e32 v230, v230
	v_exp_f32_e32 v231, v231
	v_mul_f32_e32 v232, v47, v99
	v_mul_f32_e32 v233, v39, v99
	v_add_f32_e32 v230, 1.0, v230
	v_add_f32_e32 v231, 1.0, v231
	v_rcp_f32_e32 v230, v230
	v_rcp_f32_e32 v231, v231
	v_mul_f32_e32 v228, v228, v230
	v_mul_f32_e32 v229, v229, v231
	v_mul_f32_e32 v232, v232, v228
	v_mul_f32_e32 v233, v233, v229
	v_cvt_pk_bf16_f32 v235, v232, v233
	global_store_dword v[174:175], v235, off
	v_lshl_add_u64 v[174:175], v[174:175], 0, s[98:99]
	v_mul_f32_e32 v228, v44, v100
	v_mul_f32_e32 v229, v36, v100
	v_mul_f32_e32 v230, 0xbfb8aa3b, v228
	v_mul_f32_e32 v231, 0xbfb8aa3b, v229
	v_exp_f32_e32 v230, v230
	v_exp_f32_e32 v231, v231
	v_mul_f32_e32 v232, v48, v100
	v_mul_f32_e32 v233, v40, v100
	v_add_f32_e32 v230, 1.0, v230
	v_add_f32_e32 v231, 1.0, v231
	v_rcp_f32_e32 v230, v230
	v_rcp_f32_e32 v231, v231
	v_mul_f32_e32 v228, v228, v230
	v_mul_f32_e32 v229, v229, v231
	v_mul_f32_e32 v232, v232, v228
	v_mul_f32_e32 v233, v233, v229
	v_cvt_pk_bf16_f32 v234, v232, v233
	global_store_dword v[174:175], v234, off
	v_lshl_add_u64 v[174:175], v[174:175], 0, s[98:99]
	v_mul_f32_e32 v228, v45, v101
	v_mul_f32_e32 v229, v37, v101
	v_mul_f32_e32 v230, 0xbfb8aa3b, v228
	v_mul_f32_e32 v231, 0xbfb8aa3b, v229
	v_exp_f32_e32 v230, v230
	v_exp_f32_e32 v231, v231
	v_mul_f32_e32 v232, v49, v101
	v_mul_f32_e32 v233, v41, v101
	v_add_f32_e32 v230, 1.0, v230
	v_add_f32_e32 v231, 1.0, v231
	v_rcp_f32_e32 v230, v230
	v_rcp_f32_e32 v231, v231
	v_mul_f32_e32 v228, v228, v230
	v_mul_f32_e32 v229, v229, v231
	v_mul_f32_e32 v232, v232, v228
	v_mul_f32_e32 v233, v233, v229
	v_cvt_pk_bf16_f32 v235, v232, v233
	global_store_dword v[174:175], v235, off
	v_lshl_add_u64 v[174:175], v[174:175], 0, s[98:99]
	v_lshl_add_u64 v[174:175], v[174:175], 0, s[44:45]
	v_mul_f32_e32 v228, v26, v78
	v_mul_f32_e32 v229, v18, v78
	v_mul_f32_e32 v230, 0xbfb8aa3b, v228
	v_mul_f32_e32 v231, 0xbfb8aa3b, v229
	v_exp_f32_e32 v230, v230
	v_exp_f32_e32 v231, v231
	v_mul_f32_e32 v232, v30, v78
	v_mul_f32_e32 v233, v22, v78
	v_add_f32_e32 v230, 1.0, v230
	v_add_f32_e32 v231, 1.0, v231
	v_rcp_f32_e32 v230, v230
	v_rcp_f32_e32 v231, v231
	v_mul_f32_e32 v228, v228, v230
	v_mul_f32_e32 v229, v229, v231
	v_mul_f32_e32 v232, v232, v228
	v_mul_f32_e32 v233, v233, v229
	v_cvt_pk_bf16_f32 v234, v232, v233
	global_store_dword v[174:175], v234, off
	v_lshl_add_u64 v[174:175], v[174:175], 0, s[98:99]
	v_mul_f32_e32 v228, v27, v79
	v_mul_f32_e32 v229, v19, v79
	v_mul_f32_e32 v230, 0xbfb8aa3b, v228
	v_mul_f32_e32 v231, 0xbfb8aa3b, v229
	v_exp_f32_e32 v230, v230
	v_exp_f32_e32 v231, v231
	v_mul_f32_e32 v232, v31, v79
	v_mul_f32_e32 v233, v23, v79
	v_add_f32_e32 v230, 1.0, v230
	v_add_f32_e32 v231, 1.0, v231
	v_rcp_f32_e32 v230, v230
	v_rcp_f32_e32 v231, v231
	v_mul_f32_e32 v228, v228, v230
	v_mul_f32_e32 v229, v229, v231
	v_mul_f32_e32 v232, v232, v228
	v_mul_f32_e32 v233, v233, v229
	v_cvt_pk_bf16_f32 v235, v232, v233
	global_store_dword v[174:175], v235, off
	v_lshl_add_u64 v[174:175], v[174:175], 0, s[98:99]
	v_mul_f32_e32 v228, v28, v80
	v_mul_f32_e32 v229, v20, v80
	v_mul_f32_e32 v230, 0xbfb8aa3b, v228
	v_mul_f32_e32 v231, 0xbfb8aa3b, v229
	v_exp_f32_e32 v230, v230
	v_exp_f32_e32 v231, v231
	v_mul_f32_e32 v232, v32, v80
	v_mul_f32_e32 v233, v24, v80
	v_add_f32_e32 v230, 1.0, v230
	v_add_f32_e32 v231, 1.0, v231
	v_rcp_f32_e32 v230, v230
	v_rcp_f32_e32 v231, v231
	v_mul_f32_e32 v228, v228, v230
	v_mul_f32_e32 v229, v229, v231
	v_mul_f32_e32 v232, v232, v228
	v_mul_f32_e32 v233, v233, v229
	v_cvt_pk_bf16_f32 v234, v232, v233
	global_store_dword v[174:175], v234, off
	v_lshl_add_u64 v[174:175], v[174:175], 0, s[98:99]
	v_mul_f32_e32 v228, v29, v81
	v_mul_f32_e32 v229, v21, v81
	v_mul_f32_e32 v230, 0xbfb8aa3b, v228
	v_mul_f32_e32 v231, 0xbfb8aa3b, v229
	v_exp_f32_e32 v230, v230
	v_exp_f32_e32 v231, v231
	v_mul_f32_e32 v232, v33, v81
	v_mul_f32_e32 v233, v25, v81
	v_add_f32_e32 v230, 1.0, v230
	v_add_f32_e32 v231, 1.0, v231
	v_rcp_f32_e32 v230, v230
	v_rcp_f32_e32 v231, v231
	v_mul_f32_e32 v228, v228, v230
	v_mul_f32_e32 v229, v229, v231
	v_mul_f32_e32 v232, v232, v228
	v_mul_f32_e32 v233, v233, v229
	v_cvt_pk_bf16_f32 v235, v232, v233
	global_store_dword v[174:175], v235, off
	v_lshl_add_u64 v[174:175], v[174:175], 0, s[98:99]
	v_lshl_add_u64 v[174:175], v[174:175], 0, s[44:45]
	v_mul_f32_e32 v228, v10, v58
	v_mul_f32_e32 v229, v2, v58
	v_mul_f32_e32 v230, 0xbfb8aa3b, v228
	v_mul_f32_e32 v231, 0xbfb8aa3b, v229
	v_exp_f32_e32 v230, v230
	v_exp_f32_e32 v231, v231
	v_mul_f32_e32 v232, v14, v58
	v_mul_f32_e32 v233, v6, v58
	v_add_f32_e32 v230, 1.0, v230
	v_add_f32_e32 v231, 1.0, v231
	v_rcp_f32_e32 v230, v230
	v_rcp_f32_e32 v231, v231
	v_mul_f32_e32 v228, v228, v230
	v_mul_f32_e32 v229, v229, v231
	v_mul_f32_e32 v232, v232, v228
	v_mul_f32_e32 v233, v233, v229
	v_cvt_pk_bf16_f32 v234, v232, v233
	global_store_dword v[174:175], v234, off
	v_lshl_add_u64 v[174:175], v[174:175], 0, s[98:99]
	v_mul_f32_e32 v228, v11, v59
	v_mul_f32_e32 v229, v3, v59
	v_mul_f32_e32 v230, 0xbfb8aa3b, v228
	v_mul_f32_e32 v231, 0xbfb8aa3b, v229
	v_exp_f32_e32 v230, v230
	v_exp_f32_e32 v231, v231
	v_mul_f32_e32 v232, v15, v59
	v_mul_f32_e32 v233, v7, v59
	v_add_f32_e32 v230, 1.0, v230
	v_add_f32_e32 v231, 1.0, v231
	v_rcp_f32_e32 v230, v230
	v_rcp_f32_e32 v231, v231
	v_mul_f32_e32 v228, v228, v230
	v_mul_f32_e32 v229, v229, v231
	v_mul_f32_e32 v232, v232, v228
	v_mul_f32_e32 v233, v233, v229
	v_cvt_pk_bf16_f32 v235, v232, v233
	global_store_dword v[174:175], v235, off
	v_lshl_add_u64 v[174:175], v[174:175], 0, s[98:99]
	v_mul_f32_e32 v228, v12, v60
	v_mul_f32_e32 v229, v4, v60
	v_mul_f32_e32 v230, 0xbfb8aa3b, v228
	v_mul_f32_e32 v231, 0xbfb8aa3b, v229
	v_exp_f32_e32 v230, v230
	v_exp_f32_e32 v231, v231
	v_mul_f32_e32 v232, v16, v60
	v_mul_f32_e32 v233, v8, v60
	v_add_f32_e32 v230, 1.0, v230
	v_add_f32_e32 v231, 1.0, v231
	v_rcp_f32_e32 v230, v230
	v_rcp_f32_e32 v231, v231
	v_mul_f32_e32 v228, v228, v230
	v_mul_f32_e32 v229, v229, v231
	v_mul_f32_e32 v232, v232, v228
	v_mul_f32_e32 v233, v233, v229
	v_cvt_pk_bf16_f32 v234, v232, v233
	global_store_dword v[174:175], v234, off
	v_lshl_add_u64 v[174:175], v[174:175], 0, s[98:99]
	v_mul_f32_e32 v228, v13, v61
	v_mul_f32_e32 v229, v5, v61
	v_mul_f32_e32 v230, 0xbfb8aa3b, v228
	v_mul_f32_e32 v231, 0xbfb8aa3b, v229
	v_exp_f32_e32 v230, v230
	v_exp_f32_e32 v231, v231
	v_mul_f32_e32 v232, v17, v61
	v_mul_f32_e32 v233, v9, v61
	v_add_f32_e32 v230, 1.0, v230
	v_add_f32_e32 v231, 1.0, v231
	v_rcp_f32_e32 v230, v230
	v_rcp_f32_e32 v231, v231
	v_mul_f32_e32 v228, v228, v230
	v_mul_f32_e32 v229, v229, v231
	v_mul_f32_e32 v232, v232, v228
	v_mul_f32_e32 v233, v233, v229
	v_cvt_pk_bf16_f32 v235, v232, v233
	global_store_dword v[174:175], v235, off
	v_lshl_add_u64 v[174:175], v[174:175], 0, s[98:99]
	v_lshl_add_u64 v[174:175], v[174:175], 0, s[44:45]
.Lsw_epi_done:
	s_andn2_b64 vcc, exec, s[10:11]
	s_mov_b64 s[8:9], -1
	s_cbranch_vccnz .LBB0_422
.LBB0_566:
	s_waitcnt vmcnt(0)
	v_add_f32_e32 v2, v50, v51
	v_add_f32_e32 v3, v52, v53
	v_add_f32_e32 v2, v2, v3
	v_add_f32_e32 v3, v54, v55
	v_add_f32_e32 v4, v56, v57
	v_add_f32_e32 v3, v3, v4
	v_add_f32_e32 v2, v2, v3
	s_xor_b32 s30, s30, 1
	s_nop 0
	v_mov_b32_dpp v3, v2 quad_perm:[1,0,3,2] row_mask:0xf bank_mask:0xf bound_ctrl:1
	s_and_saveexec_b64 s[8:9], s[6:7]
	s_xor_b64 s[8:9], exec, s[8:9]
	s_cbranch_execz .LBB0_421
	v_add_f32_e32 v2, v2, v3
	v_fmamk_f32 v2, v2, 0x3a800000, v181
	s_mov_b32 s2, 0x800000
	v_mul_f32_e32 v3, 0x4b800000, v2
	v_cmp_gt_f32_e32 vcc, s2, v2
	s_nop 1
	v_cndmask_b32_e32 v2, v2, v3, vcc
	v_rsq_f32_e32 v2, v2
	s_nop 0
	v_mul_f32_e32 v3, 0x45800000, v2
	v_cndmask_b32_e32 v2, v2, v3, vcc
	v_lshl_add_u32 v3, s30, 10, v206
	ds_write_b32 v3, v2
	s_branch .LBB0_421
